# stack3 + attention work queue in longest-first order: counter value remapped so the 80 two-tile edge items (n=0,31) are dealt last
# baseline (speedup 1.0000x reference)
; #define LAS __attribute__((address_space(3)))
; DI void phase_attn(const Params& P, int l, LAS unsigned char* lds) {
;     ...
;     unsigned* qctr = (unsigned*)(P.ws + WS_CTL) + 3584 + 64 * l;
;     volatile LAS int* slot = (volatile LAS int*)(lds + AT_END);
;     if (tid == 0) { const int a0 = (int)__hip_atomic_fetch_add(qctr, 1u, __ATOMIC_RELAXED, __HIP_MEMORY_SCOPE_AGENT); const int a1 = (int)__hip_atomic_fetch_add(qctr, 1u, __ATOMIC_RELAXED, __HIP_MEMORY_SCOPE_AGENT); slot[0] = a0; slot[1] = a1; }
;     __syncthreads();
;     int item = slot[0], inext = slot[1]; int pend = AT_NITEM;
;     if (item >= AT_NITEM) return;
;     int e = 0;
;     { const int n0 = (item >> 2) & 31; __syncthreads(); AT_ISSUE(item, n0 == 0 ? 1 : 0, 0); }
;     bf16x8 qr[8];
;     ...
;     AT_QLOAD(item);
.LBB0_469:
	s_or_b64 exec, exec, s[4:5]
	s_add_i32 s4, 0, 0x24000
	v_mov_b32_e32 v3, s4
	s_add_i32 s4, 0, 0x24004
	s_waitcnt lgkmcnt(0)
	s_barrier
	ds_read_b32 v3, v3
	v_mov_b32_e32 v5, s4
	ds_read_b32 v5, v5
	s_movk_i32 s4, 0x4ff
	s_mov_b32 s5, 0
	s_waitcnt lgkmcnt(1)
	v_cmp_lt_i32_e32 vcc, s4, v3
	v_readfirstlane_b32 s22, v3
	s_waitcnt lgkmcnt(0)
	v_readfirstlane_b32 s30, v5
	s_cbranch_vccnz .LBB0_501
	s_and_b32 s95, s22, 3
	s_lshr_b32 s96, s22, 2
	s_mul_i32 s97, s96, 0x889
	s_lshr_b32 s97, s97, 16
	s_mul_i32 s69, s97, 30
	s_sub_i32 s69, s96, s69
	s_add_i32 s69, s69, 1
	s_lshl_b32 s97, s97, 7
	s_lshl_b32 s69, s69, 2
	s_or_b32 s97, s97, s69
	s_or_b32 s97, s97, s95
	s_sub_i32 s96, s22, 0x4b0
	s_lshr_b32 s69, s96, 2
	s_and_b32 s96, s69, 1
	s_mul_i32 s96, s96, 0x7c
	s_lshr_b32 s69, s69, 1
	s_lshl_b32 s69, s69, 7
	s_or_b32 s69, s69, s96
	s_or_b32 s69, s69, s95
	s_cmp_lt_u32 s22, 0x4b0
	s_cselect_b32 s97, s97, s69
	s_cmp_lt_u32 s22, 0x500
	s_cselect_b32 s22, s97, s22
	s_and_b32 s95, s30, 3
	s_lshr_b32 s96, s30, 2
	s_mul_i32 s97, s96, 0x889
	s_lshr_b32 s97, s97, 16
	s_mul_i32 s69, s97, 30
	s_sub_i32 s69, s96, s69
	s_add_i32 s69, s69, 1
	s_lshl_b32 s97, s97, 7
	s_lshl_b32 s69, s69, 2
	s_or_b32 s97, s97, s69
	s_or_b32 s97, s97, s95
	s_sub_i32 s96, s30, 0x4b0
	s_lshr_b32 s69, s96, 2
	s_and_b32 s96, s69, 1
	s_mul_i32 s96, s96, 0x7c
	s_lshr_b32 s69, s69, 1
	s_lshl_b32 s69, s69, 7
	s_or_b32 s69, s69, s96
	s_or_b32 s69, s69, s95
	s_cmp_lt_u32 s30, 0x4b0
	s_cselect_b32 s97, s97, s69
	s_cmp_lt_u32 s30, 0x500
	s_cselect_b32 s30, s97, s30
	s_lshl_b32 s18, s13, 13
	s_lshl_b32 s4, s14, 14
	s_and_b32 s19, s18, 0x2000
	s_add_u32 s6, s50, s6
	s_addc_u32 s7, s51, s7
	s_add_u32 s8, s50, 0x3c40000
	s_addc_u32 s9, s51, 0
	s_add_u32 s10, s50, 0x1f940000
	s_addc_u32 s11, s51, 0
	s_ashr_i32 s14, s22, 7
	s_bfe_u32 s23, s22, 0x10001
	s_ashr_i32 s15, s14, 31
	s_add_i32 s20, 0, 0x8000
	s_bfe_u32 s21, s22, 0x50002
	s_mul_i32 s16, s23, 0xa000
	s_lshl_b64 s[14:15], s[14:15], 12
	s_add_u32 s24, s14, s16
	s_addc_u32 s25, s15, 0
	v_sub_co_u32_e64 v3, s[16:17], s21, 1
	s_nop 0
	v_readfirstlane_b32 s26, v3
	s_cmp_lg_u64 s[16:17], 0
	s_addc_u32 s16, s26, 0
	s_lshl_b32 s16, s16, 7
	s_ashr_i32 s17, s16, 31
	s_add_u32 s16, s24, s16
	s_addc_u32 s17, s25, s17
	s_lshl_b64 s[16:17], s[16:17], 8
	v_mov_b32_e32 v159, 0
	s_add_u32 s16, s6, s16
	s_addc_u32 s17, s7, s17
	s_add_i32 s31, s19, 0
	v_mov_b32_e32 v149, v159
	s_add_i32 s31, s31, s4
	v_lshlrev_b64 v[8:9], 1, v[148:149]
	v_lshl_add_u64 v[10:11], s[16:17], 0, v[8:9]
	s_mov_b32 m0, s31
	v_mov_b32_e32 v151, v159
	s_barrier
	global_load_lds_dwordx4 v[10:11], off
	v_lshlrev_b64 v[10:11], 1, v[150:151]
	v_lshl_add_u64 v[12:13], s[16:17], 0, v[10:11]
	s_add_i32 m0, s31, 0x400
	v_mov_b32_e32 v153, v159
	global_load_lds_dwordx4 v[12:13], off
	v_lshlrev_b64 v[12:13], 1, v[152:153]
	v_lshl_add_u64 v[14:15], s[16:17], 0, v[12:13]
	s_add_i32 m0, s31, 0x800
	v_mov_b32_e32 v155, v159
	global_load_lds_dwordx4 v[14:15], off
	v_lshlrev_b64 v[14:15], 1, v[154:155]
	v_lshl_add_u64 v[16:17], s[16:17], 0, v[14:15]
	s_add_i32 m0, s31, 0xc00
	v_mov_b32_e32 v157, v159
	global_load_lds_dwordx4 v[16:17], off
	v_lshlrev_b64 v[16:17], 1, v[156:157]
	v_lshl_add_u64 v[18:19], s[16:17], 0, v[16:17]
	s_add_i32 m0, s31, 0x1000
	v_mov_b32_e32 v3, v159
	global_load_lds_dwordx4 v[18:19], off
	v_lshlrev_b64 v[18:19], 1, v[158:159]
	v_lshl_add_u64 v[20:21], s[16:17], 0, v[18:19]
	s_add_i32 m0, s31, 0x1400
	v_lshlrev_b64 v[2:3], 1, v[2:3]
	v_mov_b32_e32 v5, v159
	global_load_lds_dwordx4 v[20:21], off
	v_lshl_add_u64 v[20:21], s[16:17], 0, v[2:3]
	s_add_i32 m0, s31, 0x1800
	v_lshlrev_b64 v[4:5], 1, v[4:5]
	s_lshr_b32 s35, s12, 8
	s_lshl_b32 s4, s13, 5
	global_load_lds_dwordx4 v[20:21], off
	v_lshl_add_u64 v[20:21], s[16:17], 0, v[4:5]
	s_lshl_b32 s16, s35, 6
	s_and_b32 s17, s4, 0x60
	s_xor_b32 s36, s17, s16
	s_lshl_b32 s4, s21, 7
	s_add_i32 m0, s31, 0x1c00
	s_add_i32 s37, s18, 0
	s_add_i32 s4, s4, s36
	s_add_u32 s4, s14, s4
	s_movk_i32 s34, 0x1400
	global_load_lds_dwordx4 v[20:21], off
	v_or_b32_e32 v7, s4, v1
	v_mov_b64_e32 v[20:21], s[8:9]
	v_mad_u64_u32 v[20:21], s[12:13], v7, s34, v[20:21]
	s_addc_u32 s14, s15, 0
	s_lshl_b32 s12, s22, 1
	s_and_b32 s12, s12, 2
	s_add_i32 s12, s12, s35
	v_mov_b32_e32 v207, 0x1400
	s_lshl_b32 s4, s23, 9
	s_lshl_b32 s12, s12, 7
	v_mad_i32_i24 v21, s14, v207, v21
	s_add_i32 s4, s12, s4
	v_lshl_add_u64 v[20:21], s[4:5], 1, v[20:21]
	v_mov_b32_e32 v147, v159
	v_lshl_add_u64 v[20:21], v[20:21], 0, v[146:147]
	global_load_dwordx4 v[98:101], v[20:21], off offset:224 nt
	global_load_dwordx4 v[102:105], v[20:21], off offset:192 nt
	global_load_dwordx4 v[106:109], v[20:21], off offset:160 nt
	global_load_dwordx4 v[110:113], v[20:21], off offset:128 nt
	global_load_dwordx4 v[114:117], v[20:21], off offset:96 nt
	global_load_dwordx4 v[118:121], v[20:21], off offset:64 nt
	global_load_dwordx4 v[122:125], v[20:21], off offset:32 nt
	global_load_dwordx4 v[126:129], v[20:21], off nt
	v_lshl_add_u64 v[168:169], s[6:7], 0, v[2:3]
	v_mov_b32_e32 v3, s16
	v_bitop3_b32 v3, s17, v1, v3 bitop3:0xde
	v_lshlrev_b32_e32 v7, 4, v137
	v_lshl_or_b32 v2, s35, 11, v146
	v_lshlrev_b32_e32 v3, 2, v3
	v_and_b32_e32 v21, 0xc0, v7
	v_lshlrev_b32_e32 v22, 1, v137
	s_movk_i32 s39, 0x70
	v_sub_u32_e32 v2, v2, v3
	s_movk_i32 s38, 0xc0
	v_and_b32_e32 v20, 0x78, v6
	v_and_b32_e32 v6, 0x118, v6
	v_and_b32_e32 v23, 0x70, v7
	v_bitop3_b32 v147, v146, v7, s39 bitop3:0x78
	s_movk_i32 s40, 0x60
	s_movk_i32 s41, 0x80
	s_movk_i32 s42, 0xa0
	s_movk_i32 s43, 0xe0
	v_and_or_b32 v7, v22, 32, v21
	v_add_u32_e32 v216, 0, v2
	v_mbcnt_lo_u32_b32 v2, -1, 0
	v_lshlrev_b32_e32 v160, 3, v202
	v_lshrrev_b32_e32 v162, 4, v161
	v_bitop3_b32 v208, v146, v23, 32 bitop3:0x36
	v_bitop3_b32 v209, v146, v23, 64 bitop3:0x36
	v_bitop3_b32 v210, v146, v23, s40 bitop3:0x36
	v_bitop3_b32 v211, v146, v23, s41 bitop3:0x36
	v_bitop3_b32 v212, v146, v23, s42 bitop3:0x36
	v_bitop3_b32 v213, v146, v23, s38 bitop3:0x36
	v_bitop3_b32 v214, v146, v23, s43 bitop3:0x36
	v_add3_u32 v215, v6, s20, v7
	v_lshl_add_u64 v[164:165], s[6:7], 0, v[4:5]
	v_lshl_add_u64 v[166:167], s[6:7], 0, v[18:19]
	v_lshl_add_u64 v[170:171], s[6:7], 0, v[8:9]
	v_lshl_add_u64 v[172:173], s[6:7], 0, v[10:11]
	v_lshl_add_u64 v[174:175], s[6:7], 0, v[12:13]
	v_lshl_add_u64 v[176:177], s[6:7], 0, v[14:15]
	v_lshl_add_u64 v[178:179], s[6:7], 0, v[16:17]
	v_mov_b32_e32 v218, 0x500
	v_lshlrev_b32_e32 v158, 1, v20
	s_mov_b64 s[12:13], 0xac00
	s_mov_b64 s[14:15], 0xfc00
	s_add_i32 s44, 0, 0x24008
	s_mov_b32 s45, 0x10000
	s_mov_b32 s74, 0xf149f2ca
	s_mov_b32 s75, 0x41000000
	s_movk_i32 s76, 0x4000
	s_mov_b32 s77, 0x14000
	s_movk_i32 s78, 0x50
	s_movk_i32 s79, 0x90
	s_movk_i32 s80, 0xb0
	s_movk_i32 s81, 0xd0
	s_movk_i32 s82, 0xf0
	s_mov_b32 s83, 0xc000
	s_mov_b32 s84, 0x18000
	v_mbcnt_hi_u32_b32 v217, -1, v2
	s_mov_b32 s85, 0
	s_waitcnt vmcnt(0)
	s_branch .LBB0_472
; #define LAS __attribute__((address_space(3)))
; DI unsigned cvt_pk_bf16(float lo, float hi) { unsigned r; asm volatile("v_cvt_pk_bf16_f32 %0, %1, %2" : "=v"(r) : "v"(lo), "v"(hi)); return r; }
; DI void phase_attn(const Params& P, int l, LAS unsigned char* lds) {
;     ...
;         if (inext < AT_NITEM) AT_QLOAD(inext);
;         const float rl = __builtin_amdgcn_rcpf(l_run);
; #pragma unroll
;         for (int it = 4; it < 8; ++it) zz[it] = __builtin_nontemporal_load((const u32x4*)(zp + (size_t)it * 4 * 2560));
;         asm volatile("s_waitcnt lgkmcnt(0)" ::: "memory"); __builtin_amdgcn_s_barrier(); asm volatile("" ::: "memory");
;         { LAS unsigned char* stg = lds + ((e & 1) ^ 1) * AT_BUF + wid * 8192; int rsw = r32 & 15, lsw = lane; asm volatile("" : "+v"(rsw), "+v"(lsw));
; #pragma unroll
;           for (int d0 = 0; d0 < 4; ++d0)
; #pragma unroll
;               for (int a4 = 0; a4 < 4; ++a4) { u32x2 w; w.x = cvt_pk_bf16(o[d0][a4 * 4 + 0] * rl, o[d0][a4 * 4 + 1] * rl); w.y = cvt_pk_bf16(o[d0][a4 * 4 + 2] * rl, o[d0][a4 * 4 + 3] * rl);
;                   *(LAS u32x2*)(stg + r32 * 256 + (((d0 * 4 + a4) ^ rsw) << 4) + hi * 8) = w; }
.LBB0_471:
	v_add_co_u32_e32 v66, vcc, 0x14000, v182
	v_rcp_f32_e32 v83, v222
	s_nop 0
	v_addc_co_u32_e32 v67, vcc, 0, v183, vcc
	v_add_co_u32_e32 v68, vcc, 0x19000, v182
	s_add_i32 s85, s85, s88
	s_nop 0
	v_addc_co_u32_e32 v69, vcc, 0, v183, vcc
	global_load_dwordx4 v[78:81], v[66:67], off nt
	global_load_dwordx4 v[74:77], v[68:69], off nt
	v_add_co_u32_e32 v66, vcc, 0x1e000, v182
	s_not_b32 s4, s85
	s_nop 0
	v_addc_co_u32_e32 v67, vcc, 0, v183, vcc
	v_add_co_u32_e32 v68, vcc, 0x23000, v182
	s_lshl_b32 s4, s4, 16
	s_nop 0
	v_addc_co_u32_e32 v69, vcc, 0, v183, vcc
	s_and_b32 s4, s4, 0x10000
	v_mov_b32_e32 v84, v163
	v_mov_b32_e32 v82, v161
	v_mul_f32_e32 v50, v50, v83
	v_mul_f32_e32 v51, v51, v83
	global_load_dwordx4 v[70:73], v[66:67], off nt
	s_nop 0
	global_load_dwordx4 v[66:69], v[68:69], off nt
	s_waitcnt lgkmcnt(0)
	s_barrier
	s_add_i32 s18, s37, s4
	v_cvt_pk_bf16_f32 v50, v50, v51
	v_mul_f32_e32 v51, v52, v83
	v_mul_f32_e32 v52, v53, v83
	v_add3_u32 v85, s18, v205, v160
	v_cvt_pk_bf16_f32 v51, v51, v52
	v_lshlrev_b32_e32 v52, 4, v84
	v_add_u32_e32 v53, v85, v52
	ds_write_b64 v53, v[50:51]
	v_mul_f32_e32 v50, v54, v83
	v_mul_f32_e32 v51, v55, v83
	v_cvt_pk_bf16_f32 v50, v50, v51
	v_mul_f32_e32 v51, v56, v83
	v_mul_f32_e32 v53, v57, v83
	v_cvt_pk_bf16_f32 v51, v51, v53
	v_xad_u32 v53, v52, 16, v85
	ds_write_b64 v53, v[50:51]
	v_mul_f32_e32 v50, v58, v83
	v_mul_f32_e32 v51, v59, v83
	v_cvt_pk_bf16_f32 v50, v50, v51
	v_mul_f32_e32 v51, v60, v83
	v_mul_f32_e32 v53, v61, v83
	v_cvt_pk_bf16_f32 v51, v51, v53
	v_xad_u32 v53, v52, 32, v85
	ds_write_b64 v53, v[50:51]
	v_mul_f32_e32 v50, v62, v83
	v_mul_f32_e32 v51, v63, v83
	v_cvt_pk_bf16_f32 v50, v50, v51
	v_mul_f32_e32 v51, v64, v83
	v_mul_f32_e32 v53, v65, v83
	v_cvt_pk_bf16_f32 v51, v51, v53
	v_xad_u32 v53, v52, 48, v85
	v_mul_f32_e32 v34, v34, v83
	v_mul_f32_e32 v35, v35, v83
	ds_write_b64 v53, v[50:51]
	v_cvt_pk_bf16_f32 v34, v34, v35
	v_mul_f32_e32 v35, v36, v83
	v_mul_f32_e32 v36, v37, v83
	v_cvt_pk_bf16_f32 v35, v35, v36
	v_xad_u32 v36, v52, 64, v85
	ds_write_b64 v36, v[34:35]
	v_mul_f32_e32 v34, v38, v83
	v_mul_f32_e32 v35, v39, v83
	v_cvt_pk_bf16_f32 v34, v34, v35
	v_mul_f32_e32 v35, v40, v83
	v_mul_f32_e32 v36, v41, v83
	v_cvt_pk_bf16_f32 v35, v35, v36
	v_xad_u32 v36, v52, s78, v85
	ds_write_b64 v36, v[34:35]
	v_mul_f32_e32 v34, v42, v83
	v_mul_f32_e32 v35, v43, v83
	v_cvt_pk_bf16_f32 v34, v34, v35
	v_mul_f32_e32 v35, v44, v83
	v_mul_f32_e32 v36, v45, v83
	v_cvt_pk_bf16_f32 v35, v35, v36
	v_xad_u32 v36, v52, s40, v85
	ds_write_b64 v36, v[34:35]
	v_mul_f32_e32 v34, v46, v83
	v_mul_f32_e32 v35, v47, v83
	v_cvt_pk_bf16_f32 v34, v34, v35
	v_mul_f32_e32 v35, v48, v83
	v_mul_f32_e32 v36, v49, v83
	v_cvt_pk_bf16_f32 v35, v35, v36
	v_xad_u32 v36, v52, s39, v85
	v_mul_f32_e32 v18, v18, v83
	v_mul_f32_e32 v19, v19, v83
	ds_write_b64 v36, v[34:35]
	v_cvt_pk_bf16_f32 v18, v18, v19
	v_mul_f32_e32 v19, v20, v83
	v_mul_f32_e32 v20, v21, v83
	v_cvt_pk_bf16_f32 v19, v19, v20
	v_xad_u32 v20, v52, s41, v85
	ds_write_b64 v20, v[18:19]
	v_mul_f32_e32 v18, v22, v83
	v_mul_f32_e32 v19, v23, v83
	v_cvt_pk_bf16_f32 v18, v18, v19
	v_mul_f32_e32 v19, v24, v83
	v_mul_f32_e32 v20, v25, v83
	v_cvt_pk_bf16_f32 v19, v19, v20
	v_xad_u32 v20, v52, s79, v85
	ds_write_b64 v20, v[18:19]
	v_mul_f32_e32 v18, v26, v83
	v_mul_f32_e32 v19, v27, v83
	v_cvt_pk_bf16_f32 v18, v18, v19
	v_mul_f32_e32 v19, v28, v83
	v_mul_f32_e32 v20, v29, v83
	v_cvt_pk_bf16_f32 v19, v19, v20
	v_xad_u32 v20, v52, s42, v85
	ds_write_b64 v20, v[18:19]
	v_mul_f32_e32 v18, v30, v83
	v_mul_f32_e32 v19, v31, v83
	v_cvt_pk_bf16_f32 v18, v18, v19
	v_mul_f32_e32 v19, v32, v83
	v_mul_f32_e32 v20, v33, v83
	v_cvt_pk_bf16_f32 v19, v19, v20
	v_xad_u32 v20, v52, s80, v85
	v_mul_f32_e32 v2, v2, v83
	v_mul_f32_e32 v3, v3, v83
	ds_write_b64 v20, v[18:19]
	v_cvt_pk_bf16_f32 v2, v2, v3
	v_mul_f32_e32 v3, v4, v83
	v_mul_f32_e32 v4, v5, v83
	v_cvt_pk_bf16_f32 v3, v3, v4
	v_xad_u32 v4, v52, s38, v85
	ds_write_b64 v4, v[2:3]
	v_mul_f32_e32 v2, v6, v83
	v_mul_f32_e32 v3, v7, v83
	v_cvt_pk_bf16_f32 v2, v2, v3
	v_mul_f32_e32 v3, v8, v83
	v_mul_f32_e32 v4, v9, v83
	v_cvt_pk_bf16_f32 v3, v3, v4
	v_xad_u32 v4, v52, s81, v85
	ds_write_b64 v4, v[2:3]
	v_mul_f32_e32 v2, v10, v83
	v_mul_f32_e32 v3, v11, v83
	v_cvt_pk_bf16_f32 v2, v2, v3
	v_mul_f32_e32 v3, v12, v83
	v_mul_f32_e32 v4, v13, v83
	v_cvt_pk_bf16_f32 v3, v3, v4
	v_xad_u32 v4, v52, s43, v85
	ds_write_b64 v4, v[2:3]
	v_mul_f32_e32 v2, v14, v83
	v_mul_f32_e32 v3, v15, v83
	v_cvt_pk_bf16_f32 v2, v2, v3
	v_mul_f32_e32 v3, v16, v83
	v_mul_f32_e32 v4, v17, v83
	v_cvt_pk_bf16_f32 v3, v3, v4
	v_xad_u32 v4, v52, s82, v85
	s_waitcnt vmcnt(0)
	v_lshlrev_b32_e32 v10, 16, v142
	v_and_b32_e32 v12, 0xffff0000, v142
	ds_write_b64 v4, v[2:3]
	v_ashrrev_i32_e32 v4, 4, v82
	v_mul_f32_e32 v11, 0xbfb8aa3b, v10
	v_mul_f32_e32 v13, 0xbfb8aa3b, v12
	v_xor_b32_e32 v6, v4, v82
	v_exp_f32_e32 v11, v11
	v_exp_f32_e32 v13, v13
	v_lshlrev_b32_e32 v6, 4, v6
	v_lshlrev_b32_e32 v5, 8, v4
	v_and_b32_e32 v6, 0xf0, v6
	s_waitcnt lgkmcnt(0)
	v_add3_u32 v5, s18, v5, v6
	ds_read_b128 v[6:9], v5
	v_add_f32_e32 v11, 1.0, v11
	v_add_f32_e32 v13, 1.0, v13
	v_rcp_f32_e32 v11, v11
	v_rcp_f32_e32 v13, v13
	s_waitcnt lgkmcnt(0)
; #define LAS __attribute__((address_space(3)))
; DI unsigned cvt_pk_bf16(float lo, float hi) { unsigned r; asm volatile("v_cvt_pk_bf16_f32 %0, %1, %2" : "=v"(r) : "v"(lo), "v"(hi)); return r; }
; DI float bflo(unsigned w) { return __uint_as_float(w << 16); }
; DI float bfhi(unsigned w) { return __uint_as_float(w & 0xffff0000u); }
; DI float silu_fast(float z) { return z * __builtin_amdgcn_rcpf(1.0f + __builtin_amdgcn_exp2f(-z * LOG2E)); }
; DI void phase_attn(const Params& P, int l, LAS unsigned char* lds) {
;     ...
;           bf16_t* op = MI + (tokw + (lane >> 4)) * DM + g * 128 + (lane & 15) * 8;
; #pragma unroll
;           for (int it = 0; it < 8; ++it) { const int row = it * 4 + (lsw >> 4);
;               const u32x4 ov = *(const LAS u32x4*)(stg + row * 256 + (((lsw & 15) ^ (row & 15)) << 4)); const u32x4 z = zz[it]; u32x4 w;
; #pragma unroll
;               for (int q = 0; q < 4; ++q) w[q] = cvt_pk_bf16(bflo(ov[q]) * silu_fast(bflo(z[q])), bfhi(ov[q]) * silu_fast(bfhi(z[q])));
;               *(u32x4*)(op + (size_t)it * 4 * DM) = w; if (it & 1) __builtin_amdgcn_sched_barrier(0); } }
	v_lshlrev_b32_e32 v14, 16, v6
	v_and_b32_e32 v6, 0xffff0000, v6
	v_mul_f32_e32 v10, v11, v10
	v_mul_f32_e32 v11, v13, v12
	v_mul_f32_e32 v10, v10, v14
	v_mul_f32_e32 v6, v11, v6
	v_cvt_pk_bf16_f32 v6, v10, v6
	v_lshlrev_b32_e32 v10, 16, v143
	v_and_b32_e32 v12, 0xffff0000, v143
	v_mul_f32_e32 v11, 0xbfb8aa3b, v10
	v_mul_f32_e32 v13, 0xbfb8aa3b, v12
	v_exp_f32_e32 v11, v11
	v_exp_f32_e32 v13, v13
	v_lshlrev_b32_e32 v14, 16, v7
	v_and_b32_e32 v7, 0xffff0000, v7
	v_add_f32_e32 v11, 1.0, v11
	v_add_f32_e32 v13, 1.0, v13
	v_rcp_f32_e32 v11, v11
	v_rcp_f32_e32 v13, v13
	v_lshlrev_b64 v[2:3], 12, v[180:181]
	v_lshl_add_u64 v[2:3], s[10:11], 0, v[2:3]
	v_mul_f32_e32 v10, v11, v10
	v_mul_f32_e32 v11, v13, v12
	v_mul_f32_e32 v10, v10, v14
	v_mul_f32_e32 v7, v11, v7
	v_cvt_pk_bf16_f32 v7, v10, v7
	v_lshlrev_b32_e32 v10, 16, v144
	v_and_b32_e32 v12, 0xffff0000, v144
	v_mul_f32_e32 v11, 0xbfb8aa3b, v10
	v_mul_f32_e32 v13, 0xbfb8aa3b, v12
	v_exp_f32_e32 v11, v11
	v_exp_f32_e32 v13, v13
	v_lshlrev_b32_e32 v14, 16, v8
	v_and_b32_e32 v8, 0xffff0000, v8
	v_add_f32_e32 v11, 1.0, v11
	v_add_f32_e32 v13, 1.0, v13
	v_rcp_f32_e32 v11, v11
	v_rcp_f32_e32 v13, v13
	s_lshl_b32 s4, s86, 1
	v_lshl_add_u64 v[2:3], v[2:3], 0, s[4:5]
	v_mul_f32_e32 v10, v11, v10
	v_mul_f32_e32 v11, v13, v12
	v_mul_f32_e32 v10, v10, v14
	v_mul_f32_e32 v8, v11, v8
	v_cvt_pk_bf16_f32 v8, v10, v8
	v_lshlrev_b32_e32 v10, 16, v145
	v_and_b32_e32 v12, 0xffff0000, v145
	v_mul_f32_e32 v11, 0xbfb8aa3b, v10
	v_mul_f32_e32 v13, 0xbfb8aa3b, v12
	v_exp_f32_e32 v11, v11
	v_exp_f32_e32 v13, v13
	v_lshlrev_b32_e32 v14, 16, v9
	v_and_b32_e32 v9, 0xffff0000, v9
	v_add_f32_e32 v11, 1.0, v11
	v_add_f32_e32 v13, 1.0, v13
	v_rcp_f32_e32 v11, v11
	v_rcp_f32_e32 v13, v13
	v_lshl_add_u64 v[2:3], v[2:3], 0, v[158:159]
	v_mul_f32_e32 v10, v11, v10
	v_mul_f32_e32 v11, v13, v12
	v_mul_f32_e32 v10, v10, v14
	v_mul_f32_e32 v9, v11, v9
	v_cvt_pk_bf16_f32 v9, v10, v9
	v_lshlrev_b32_e32 v10, 16, v138
	v_and_b32_e32 v12, 0xffff0000, v138
	global_store_dwordx4 v[2:3], v[6:9], off
	v_mul_f32_e32 v11, 0xbfb8aa3b, v10
	v_mul_f32_e32 v13, 0xbfb8aa3b, v12
	v_add_u32_e32 v6, 4, v4
	v_lshlrev_b32_e32 v7, 8, v6
	v_xor_b32_e32 v6, v6, v82
	v_exp_f32_e32 v11, v11
	v_exp_f32_e32 v13, v13
	v_lshlrev_b32_e32 v6, 4, v6
	v_and_b32_e32 v6, 0xf0, v6
	v_add3_u32 v6, s18, v7, v6
	ds_read_b128 v[6:9], v6
	v_add_f32_e32 v11, 1.0, v11
	v_add_f32_e32 v13, 1.0, v13
	v_rcp_f32_e32 v11, v11
	v_rcp_f32_e32 v13, v13
	s_waitcnt lgkmcnt(0)
	v_lshlrev_b32_e32 v14, 16, v6
	v_and_b32_e32 v6, 0xffff0000, v6
	v_mul_f32_e32 v10, v11, v10
	v_mul_f32_e32 v11, v13, v12
	v_mul_f32_e32 v10, v10, v14
	v_mul_f32_e32 v6, v11, v6
	v_cvt_pk_bf16_f32 v6, v10, v6
	v_lshlrev_b32_e32 v10, 16, v139
	v_and_b32_e32 v12, 0xffff0000, v139
	v_mul_f32_e32 v11, 0xbfb8aa3b, v10
	v_mul_f32_e32 v13, 0xbfb8aa3b, v12
	v_exp_f32_e32 v11, v11
	v_exp_f32_e32 v13, v13
	v_lshlrev_b32_e32 v14, 16, v7
	v_and_b32_e32 v7, 0xffff0000, v7
	v_add_f32_e32 v11, 1.0, v11
	v_add_f32_e32 v13, 1.0, v13
	v_rcp_f32_e32 v11, v11
	v_rcp_f32_e32 v13, v13
	v_mul_f32_e32 v10, v11, v10
	v_mul_f32_e32 v11, v13, v12
	v_mul_f32_e32 v10, v10, v14
	v_mul_f32_e32 v7, v11, v7
	v_cvt_pk_bf16_f32 v7, v10, v7
	v_lshlrev_b32_e32 v10, 16, v140
	v_and_b32_e32 v12, 0xffff0000, v140
	v_mul_f32_e32 v11, 0xbfb8aa3b, v10
	v_mul_f32_e32 v13, 0xbfb8aa3b, v12
	v_exp_f32_e32 v11, v11
	v_exp_f32_e32 v13, v13
	v_lshlrev_b32_e32 v14, 16, v8
	v_and_b32_e32 v8, 0xffff0000, v8
	v_add_f32_e32 v11, 1.0, v11
	v_add_f32_e32 v13, 1.0, v13
	v_rcp_f32_e32 v11, v11
	v_rcp_f32_e32 v13, v13
	v_mul_f32_e32 v10, v11, v10
	v_mul_f32_e32 v11, v13, v12
	v_mul_f32_e32 v10, v10, v14
	v_mul_f32_e32 v8, v11, v8
	v_cvt_pk_bf16_f32 v8, v10, v8
	v_lshlrev_b32_e32 v10, 16, v141
	v_and_b32_e32 v12, 0xffff0000, v141
	v_mul_f32_e32 v11, 0xbfb8aa3b, v10
	v_mul_f32_e32 v13, 0xbfb8aa3b, v12
	v_exp_f32_e32 v11, v11
	v_exp_f32_e32 v13, v13
	v_lshlrev_b32_e32 v14, 16, v9
	v_and_b32_e32 v9, 0xffff0000, v9
	v_add_f32_e32 v11, 1.0, v11
	v_add_f32_e32 v13, 1.0, v13
	v_rcp_f32_e32 v11, v11
	v_rcp_f32_e32 v13, v13
	v_mul_f32_e32 v10, v11, v10
	v_mul_f32_e32 v11, v13, v12
	v_mul_f32_e32 v10, v10, v14
	v_mul_f32_e32 v9, v11, v9
	v_cvt_pk_bf16_f32 v9, v10, v9
	v_add_co_u32_e32 v10, vcc, s76, v2
	s_nop 1
	v_addc_co_u32_e32 v11, vcc, 0, v3, vcc
	global_store_dwordx4 v[10:11], v[6:9], off
	v_lshlrev_b32_e32 v10, 16, v134
	v_and_b32_e32 v12, 0xffff0000, v134
	v_add_u32_e32 v6, 8, v4
	v_mul_f32_e32 v11, 0xbfb8aa3b, v10
	v_mul_f32_e32 v13, 0xbfb8aa3b, v12
	v_lshlrev_b32_e32 v7, 8, v6
	v_xor_b32_e32 v6, v6, v82
	v_exp_f32_e32 v11, v11
	v_exp_f32_e32 v13, v13
	v_lshlrev_b32_e32 v6, 4, v6
	v_and_b32_e32 v6, 0xf0, v6
	v_add3_u32 v6, s18, v7, v6
	ds_read_b128 v[6:9], v6
	v_add_f32_e32 v11, 1.0, v11
	v_add_f32_e32 v13, 1.0, v13
	v_rcp_f32_e32 v11, v11
	v_rcp_f32_e32 v13, v13
	s_waitcnt lgkmcnt(0)
; #define LAS __attribute__((address_space(3)))
; DI unsigned cvt_pk_bf16(float lo, float hi) { unsigned r; asm volatile("v_cvt_pk_bf16_f32 %0, %1, %2" : "=v"(r) : "v"(lo), "v"(hi)); return r; }
; DI float bflo(unsigned w) { return __uint_as_float(w << 16); }
; DI float bfhi(unsigned w) { return __uint_as_float(w & 0xffff0000u); }
; DI float silu_fast(float z) { return z * __builtin_amdgcn_rcpf(1.0f + __builtin_amdgcn_exp2f(-z * LOG2E)); }
; DI void phase_attn(const Params& P, int l, LAS unsigned char* lds) {
;     ...
;           bf16_t* op = MI + (tokw + (lane >> 4)) * DM + g * 128 + (lane & 15) * 8;
; #pragma unroll
;           for (int it = 0; it < 8; ++it) { const int row = it * 4 + (lsw >> 4);
;               const u32x4 ov = *(const LAS u32x4*)(stg + row * 256 + (((lsw & 15) ^ (row & 15)) << 4)); const u32x4 z = zz[it]; u32x4 w;
; #pragma unroll
;               for (int q = 0; q < 4; ++q) w[q] = cvt_pk_bf16(bflo(ov[q]) * silu_fast(bflo(z[q])), bfhi(ov[q]) * silu_fast(bfhi(z[q])));
;               *(u32x4*)(op + (size_t)it * 4 * DM) = w; if (it & 1) __builtin_amdgcn_sched_barrier(0); } }
	v_lshlrev_b32_e32 v14, 16, v6
	v_and_b32_e32 v6, 0xffff0000, v6
	v_mul_f32_e32 v10, v11, v10
	v_mul_f32_e32 v11, v13, v12
	v_mul_f32_e32 v10, v10, v14
	v_mul_f32_e32 v6, v11, v6
	v_cvt_pk_bf16_f32 v6, v10, v6
	v_lshlrev_b32_e32 v10, 16, v135
	v_and_b32_e32 v12, 0xffff0000, v135
	v_mul_f32_e32 v11, 0xbfb8aa3b, v10
	v_mul_f32_e32 v13, 0xbfb8aa3b, v12
	v_exp_f32_e32 v11, v11
	v_exp_f32_e32 v13, v13
	v_lshlrev_b32_e32 v14, 16, v7
	v_and_b32_e32 v7, 0xffff0000, v7
	v_add_f32_e32 v11, 1.0, v11
	v_add_f32_e32 v13, 1.0, v13
	v_rcp_f32_e32 v11, v11
	v_rcp_f32_e32 v13, v13
	s_mov_b32 s4, 0x8000
	v_mul_f32_e32 v10, v11, v10
	v_mul_f32_e32 v11, v13, v12
	v_mul_f32_e32 v10, v10, v14
	v_mul_f32_e32 v7, v11, v7
	v_cvt_pk_bf16_f32 v7, v10, v7
	v_lshlrev_b32_e32 v10, 16, v136
	v_and_b32_e32 v12, 0xffff0000, v136
	v_mul_f32_e32 v11, 0xbfb8aa3b, v10
	v_mul_f32_e32 v13, 0xbfb8aa3b, v12
	v_exp_f32_e32 v11, v11
	v_exp_f32_e32 v13, v13
	v_lshlrev_b32_e32 v14, 16, v8
	v_and_b32_e32 v8, 0xffff0000, v8
	v_add_f32_e32 v11, 1.0, v11
	v_add_f32_e32 v13, 1.0, v13
	v_rcp_f32_e32 v11, v11
	v_rcp_f32_e32 v13, v13
	v_mul_f32_e32 v10, v11, v10
	v_mul_f32_e32 v11, v13, v12
	v_mul_f32_e32 v10, v10, v14
	v_mul_f32_e32 v8, v11, v8
	v_cvt_pk_bf16_f32 v8, v10, v8
	v_lshlrev_b32_e32 v10, 16, v137
	v_and_b32_e32 v12, 0xffff0000, v137
	v_mul_f32_e32 v11, 0xbfb8aa3b, v10
	v_mul_f32_e32 v13, 0xbfb8aa3b, v12
	v_exp_f32_e32 v11, v11
	v_exp_f32_e32 v13, v13
	v_lshlrev_b32_e32 v14, 16, v9
	v_and_b32_e32 v9, 0xffff0000, v9
	v_add_f32_e32 v11, 1.0, v11
	v_add_f32_e32 v13, 1.0, v13
	v_rcp_f32_e32 v11, v11
	v_rcp_f32_e32 v13, v13
	v_mul_f32_e32 v10, v11, v10
	v_mul_f32_e32 v11, v13, v12
	v_mul_f32_e32 v10, v10, v14
	v_mul_f32_e32 v9, v11, v9
	v_cvt_pk_bf16_f32 v9, v10, v9
	v_add_co_u32_e32 v10, vcc, s4, v2
	v_and_b32_e32 v12, 0xffff0000, v130
	s_nop 0
	v_addc_co_u32_e32 v11, vcc, 0, v3, vcc
	global_store_dwordx4 v[10:11], v[6:9], off
	v_lshlrev_b32_e32 v10, 16, v130
	v_mul_f32_e32 v11, 0xbfb8aa3b, v10
	v_add_u32_e32 v6, 12, v4
	v_mul_f32_e32 v13, 0xbfb8aa3b, v12
	v_lshlrev_b32_e32 v7, 8, v6
	v_xor_b32_e32 v6, v6, v82
	v_exp_f32_e32 v11, v11
	v_exp_f32_e32 v13, v13
	v_lshlrev_b32_e32 v6, 4, v6
	v_and_b32_e32 v6, 0xf0, v6
	v_add3_u32 v6, s18, v7, v6
	ds_read_b128 v[6:9], v6
	v_add_f32_e32 v11, 1.0, v11
	v_add_f32_e32 v13, 1.0, v13
	v_rcp_f32_e32 v11, v11
	v_rcp_f32_e32 v13, v13
	s_waitcnt lgkmcnt(0)
	v_lshlrev_b32_e32 v14, 16, v6
	v_and_b32_e32 v6, 0xffff0000, v6
	v_mul_f32_e32 v10, v11, v10
	v_mul_f32_e32 v11, v13, v12
	v_mul_f32_e32 v10, v10, v14
	v_mul_f32_e32 v6, v11, v6
	v_cvt_pk_bf16_f32 v6, v10, v6
	v_lshlrev_b32_e32 v10, 16, v131
	v_and_b32_e32 v12, 0xffff0000, v131
	v_mul_f32_e32 v11, 0xbfb8aa3b, v10
	v_mul_f32_e32 v13, 0xbfb8aa3b, v12
	v_exp_f32_e32 v11, v11
	v_exp_f32_e32 v13, v13
	v_lshlrev_b32_e32 v14, 16, v7
	v_and_b32_e32 v7, 0xffff0000, v7
	v_add_f32_e32 v11, 1.0, v11
	v_add_f32_e32 v13, 1.0, v13
	v_rcp_f32_e32 v11, v11
	v_rcp_f32_e32 v13, v13
	v_mul_f32_e32 v10, v11, v10
	v_mul_f32_e32 v11, v13, v12
	v_mul_f32_e32 v10, v10, v14
	v_mul_f32_e32 v7, v11, v7
	v_cvt_pk_bf16_f32 v7, v10, v7
	v_lshlrev_b32_e32 v10, 16, v132
	v_and_b32_e32 v12, 0xffff0000, v132
	v_mul_f32_e32 v11, 0xbfb8aa3b, v10
	v_mul_f32_e32 v13, 0xbfb8aa3b, v12
	v_exp_f32_e32 v11, v11
	v_exp_f32_e32 v13, v13
	v_lshlrev_b32_e32 v14, 16, v8
	v_and_b32_e32 v8, 0xffff0000, v8
	v_add_f32_e32 v11, 1.0, v11
	v_add_f32_e32 v13, 1.0, v13
	v_rcp_f32_e32 v11, v11
	v_rcp_f32_e32 v13, v13
	v_mul_f32_e32 v10, v11, v10
	v_mul_f32_e32 v11, v13, v12
	v_mul_f32_e32 v10, v10, v14
	v_mul_f32_e32 v8, v11, v8
	v_cvt_pk_bf16_f32 v8, v10, v8
	v_lshlrev_b32_e32 v10, 16, v133
	v_and_b32_e32 v12, 0xffff0000, v133
	v_mul_f32_e32 v11, 0xbfb8aa3b, v10
	v_mul_f32_e32 v13, 0xbfb8aa3b, v12
	v_exp_f32_e32 v11, v11
	v_exp_f32_e32 v13, v13
	v_lshlrev_b32_e32 v14, 16, v9
	v_and_b32_e32 v9, 0xffff0000, v9
	v_add_f32_e32 v11, 1.0, v11
	v_add_f32_e32 v13, 1.0, v13
	v_rcp_f32_e32 v11, v11
	v_rcp_f32_e32 v13, v13
	v_mul_f32_e32 v10, v11, v10
	v_mul_f32_e32 v11, v13, v12
	v_mul_f32_e32 v10, v10, v14
	v_mul_f32_e32 v9, v11, v9
	v_cvt_pk_bf16_f32 v9, v10, v9
	v_add_co_u32_e32 v10, vcc, s83, v2
	s_nop 1
	v_addc_co_u32_e32 v11, vcc, 0, v3, vcc
	global_store_dwordx4 v[10:11], v[6:9], off
	ds_read_b128 v[6:9], v5 offset:4096
	v_lshlrev_b32_e32 v5, 16, v78
	v_and_b32_e32 v11, 0xffff0000, v78
	v_mul_f32_e32 v10, 0xbfb8aa3b, v5
	v_mul_f32_e32 v12, 0xbfb8aa3b, v11
	v_exp_f32_e32 v10, v10
	v_exp_f32_e32 v12, v12
	s_waitcnt lgkmcnt(0)
; #define LAS __attribute__((address_space(3)))
; DI unsigned cvt_pk_bf16(float lo, float hi) { unsigned r; asm volatile("v_cvt_pk_bf16_f32 %0, %1, %2" : "=v"(r) : "v"(lo), "v"(hi)); return r; }
; DI float bflo(unsigned w) { return __uint_as_float(w << 16); }
; DI float bfhi(unsigned w) { return __uint_as_float(w & 0xffff0000u); }
; DI float silu_fast(float z) { return z * __builtin_amdgcn_rcpf(1.0f + __builtin_amdgcn_exp2f(-z * LOG2E)); }
; DI void phase_attn(const Params& P, int l, LAS unsigned char* lds) {
;     ...
;           bf16_t* op = MI + (tokw + (lane >> 4)) * DM + g * 128 + (lane & 15) * 8;
; #pragma unroll
;           for (int it = 0; it < 8; ++it) { const int row = it * 4 + (lsw >> 4);
;               const u32x4 ov = *(const LAS u32x4*)(stg + row * 256 + (((lsw & 15) ^ (row & 15)) << 4)); const u32x4 z = zz[it]; u32x4 w;
; #pragma unroll
;               for (int q = 0; q < 4; ++q) w[q] = cvt_pk_bf16(bflo(ov[q]) * silu_fast(bflo(z[q])), bfhi(ov[q]) * silu_fast(bfhi(z[q])));
;               *(u32x4*)(op + (size_t)it * 4 * DM) = w; if (it & 1) __builtin_amdgcn_sched_barrier(0); } }
	v_lshlrev_b32_e32 v13, 16, v6
	v_and_b32_e32 v6, 0xffff0000, v6
	v_add_f32_e32 v10, 1.0, v10
	v_add_f32_e32 v12, 1.0, v12
	v_rcp_f32_e32 v10, v10
	v_rcp_f32_e32 v12, v12
	v_mul_f32_e32 v5, v10, v5
	v_mul_f32_e32 v10, v12, v11
	v_mul_f32_e32 v5, v5, v13
	v_mul_f32_e32 v6, v10, v6
	v_cvt_pk_bf16_f32 v6, v5, v6
	v_lshlrev_b32_e32 v5, 16, v79
	v_and_b32_e32 v11, 0xffff0000, v79
	v_mul_f32_e32 v10, 0xbfb8aa3b, v5
	v_mul_f32_e32 v12, 0xbfb8aa3b, v11
	v_exp_f32_e32 v10, v10
	v_exp_f32_e32 v12, v12
	v_lshlrev_b32_e32 v13, 16, v7
	v_and_b32_e32 v7, 0xffff0000, v7
	v_add_f32_e32 v10, 1.0, v10
	v_add_f32_e32 v12, 1.0, v12
	v_rcp_f32_e32 v10, v10
	v_rcp_f32_e32 v12, v12
	v_mul_f32_e32 v5, v10, v5
	v_mul_f32_e32 v10, v12, v11
	v_mul_f32_e32 v5, v5, v13
	v_mul_f32_e32 v7, v10, v7
	v_cvt_pk_bf16_f32 v7, v5, v7
	v_lshlrev_b32_e32 v5, 16, v80
	v_and_b32_e32 v11, 0xffff0000, v80
	v_mul_f32_e32 v10, 0xbfb8aa3b, v5
	v_mul_f32_e32 v12, 0xbfb8aa3b, v11
	v_exp_f32_e32 v10, v10
	v_exp_f32_e32 v12, v12
	v_lshlrev_b32_e32 v13, 16, v8
	v_and_b32_e32 v8, 0xffff0000, v8
	v_add_f32_e32 v10, 1.0, v10
	v_add_f32_e32 v12, 1.0, v12
	v_rcp_f32_e32 v10, v10
	v_rcp_f32_e32 v12, v12
	v_mul_f32_e32 v5, v10, v5
	v_mul_f32_e32 v10, v12, v11
	v_mul_f32_e32 v5, v5, v13
	v_mul_f32_e32 v8, v10, v8
	v_cvt_pk_bf16_f32 v8, v5, v8
	v_lshlrev_b32_e32 v5, 16, v81
	v_and_b32_e32 v11, 0xffff0000, v81
	v_mul_f32_e32 v10, 0xbfb8aa3b, v5
	v_mul_f32_e32 v12, 0xbfb8aa3b, v11
	v_exp_f32_e32 v10, v10
	v_exp_f32_e32 v12, v12
	v_lshlrev_b32_e32 v13, 16, v9
	v_and_b32_e32 v9, 0xffff0000, v9
	v_add_f32_e32 v10, 1.0, v10
	v_add_f32_e32 v12, 1.0, v12
	v_rcp_f32_e32 v10, v10
	v_rcp_f32_e32 v12, v12
	v_mul_f32_e32 v5, v10, v5
	v_mul_f32_e32 v10, v12, v11
	v_mul_f32_e32 v5, v5, v13
	v_mul_f32_e32 v9, v10, v9
	v_add_co_u32_e32 v10, vcc, s45, v2
	v_cvt_pk_bf16_f32 v9, v5, v9
	v_add_u32_e32 v5, 20, v4
	s_nop 0
	v_addc_co_u32_e32 v11, vcc, 0, v3, vcc
	global_store_dwordx4 v[10:11], v[6:9], off
	v_and_b32_e32 v11, 0xffff0000, v74
	v_mul_f32_e32 v12, 0xbfb8aa3b, v11
	v_lshlrev_b32_e32 v6, 8, v5
	v_xor_b32_e32 v5, v5, v82
	v_lshlrev_b32_e32 v5, 4, v5
	v_and_b32_e32 v5, 0xf0, v5
	v_add3_u32 v5, s18, v6, v5
	ds_read_b128 v[6:9], v5
	v_lshlrev_b32_e32 v5, 16, v74
	v_mul_f32_e32 v10, 0xbfb8aa3b, v5
	v_exp_f32_e32 v10, v10
	v_exp_f32_e32 v12, v12
	s_waitcnt lgkmcnt(0)
	v_lshlrev_b32_e32 v13, 16, v6
	v_and_b32_e32 v6, 0xffff0000, v6
	v_add_f32_e32 v10, 1.0, v10
	v_add_f32_e32 v12, 1.0, v12
	v_rcp_f32_e32 v10, v10
	v_rcp_f32_e32 v12, v12
	v_mul_f32_e32 v5, v10, v5
	v_mul_f32_e32 v10, v12, v11
	v_mul_f32_e32 v5, v5, v13
	v_mul_f32_e32 v6, v10, v6
	v_cvt_pk_bf16_f32 v6, v5, v6
	v_lshlrev_b32_e32 v5, 16, v75
	v_and_b32_e32 v11, 0xffff0000, v75
	v_mul_f32_e32 v10, 0xbfb8aa3b, v5
	v_mul_f32_e32 v12, 0xbfb8aa3b, v11
	v_exp_f32_e32 v10, v10
	v_exp_f32_e32 v12, v12
	v_lshlrev_b32_e32 v13, 16, v7
	v_and_b32_e32 v7, 0xffff0000, v7
	v_add_f32_e32 v10, 1.0, v10
	v_add_f32_e32 v12, 1.0, v12
	v_rcp_f32_e32 v10, v10
	v_rcp_f32_e32 v12, v12
	v_mul_f32_e32 v5, v10, v5
	v_mul_f32_e32 v10, v12, v11
	v_mul_f32_e32 v5, v5, v13
	v_mul_f32_e32 v7, v10, v7
	v_cvt_pk_bf16_f32 v7, v5, v7
	v_lshlrev_b32_e32 v5, 16, v76
	v_and_b32_e32 v11, 0xffff0000, v76
	v_mul_f32_e32 v10, 0xbfb8aa3b, v5
	v_mul_f32_e32 v12, 0xbfb8aa3b, v11
	v_exp_f32_e32 v10, v10
	v_exp_f32_e32 v12, v12
	v_lshlrev_b32_e32 v13, 16, v8
	v_and_b32_e32 v8, 0xffff0000, v8
	v_add_f32_e32 v10, 1.0, v10
	v_add_f32_e32 v12, 1.0, v12
	v_rcp_f32_e32 v10, v10
	v_rcp_f32_e32 v12, v12
	v_mul_f32_e32 v5, v10, v5
	v_mul_f32_e32 v10, v12, v11
	v_mul_f32_e32 v5, v5, v13
	v_mul_f32_e32 v8, v10, v8
	v_cvt_pk_bf16_f32 v8, v5, v8
	v_lshlrev_b32_e32 v5, 16, v77
	v_and_b32_e32 v11, 0xffff0000, v77
	v_mul_f32_e32 v10, 0xbfb8aa3b, v5
	v_mul_f32_e32 v12, 0xbfb8aa3b, v11
	v_exp_f32_e32 v10, v10
	v_exp_f32_e32 v12, v12
	v_lshlrev_b32_e32 v13, 16, v9
	v_and_b32_e32 v9, 0xffff0000, v9
	v_add_f32_e32 v10, 1.0, v10
	v_add_f32_e32 v12, 1.0, v12
	v_rcp_f32_e32 v10, v10
	v_rcp_f32_e32 v12, v12
	v_mul_f32_e32 v5, v10, v5
	v_mul_f32_e32 v10, v12, v11
	v_mul_f32_e32 v9, v10, v9
	v_add_co_u32_e32 v10, vcc, s77, v2
	v_mul_f32_e32 v5, v5, v13
	s_nop 0
	v_addc_co_u32_e32 v11, vcc, 0, v3, vcc
	v_cvt_pk_bf16_f32 v9, v5, v9
	global_store_dwordx4 v[10:11], v[6:9], off
	v_add_u32_e32 v5, 24, v4
	s_nop 0
	v_lshlrev_b32_e32 v6, 8, v5
	v_xor_b32_e32 v5, v5, v82
	v_lshlrev_b32_e32 v5, 4, v5
	v_and_b32_e32 v5, 0xf0, v5
	v_add3_u32 v5, s18, v6, v5
	ds_read_b128 v[6:9], v5
	v_lshlrev_b32_e32 v5, 16, v70
	v_and_b32_e32 v11, 0xffff0000, v70
	v_mul_f32_e32 v10, 0xbfb8aa3b, v5
	v_mul_f32_e32 v12, 0xbfb8aa3b, v11
	v_exp_f32_e32 v10, v10
	v_exp_f32_e32 v12, v12
	s_waitcnt lgkmcnt(0)
; #define LAS __attribute__((address_space(3)))
; DI unsigned cvt_pk_bf16(float lo, float hi) { unsigned r; asm volatile("v_cvt_pk_bf16_f32 %0, %1, %2" : "=v"(r) : "v"(lo), "v"(hi)); return r; }
; DI float bflo(unsigned w) { return __uint_as_float(w << 16); }
; DI float bfhi(unsigned w) { return __uint_as_float(w & 0xffff0000u); }
; DI float silu_fast(float z) { return z * __builtin_amdgcn_rcpf(1.0f + __builtin_amdgcn_exp2f(-z * LOG2E)); }
; DI void phase_attn(const Params& P, int l, LAS unsigned char* lds) {
;     ...
;           for (int it = 0; it < 8; ++it) { const int row = it * 4 + (lsw >> 4);
;               const u32x4 ov = *(const LAS u32x4*)(stg + row * 256 + (((lsw & 15) ^ (row & 15)) << 4)); const u32x4 z = zz[it]; u32x4 w;
; #pragma unroll
;               for (int q = 0; q < 4; ++q) w[q] = cvt_pk_bf16(bflo(ov[q]) * silu_fast(bflo(z[q])), bfhi(ov[q]) * silu_fast(bfhi(z[q])));
;               *(u32x4*)(op + (size_t)it * 4 * DM) = w; if (it & 1) __builtin_amdgcn_sched_barrier(0); } }
;         item = inext; inext = slot[2];
	v_lshlrev_b32_e32 v13, 16, v6
	v_and_b32_e32 v6, 0xffff0000, v6
	v_add_f32_e32 v10, 1.0, v10
	v_add_f32_e32 v12, 1.0, v12
	v_rcp_f32_e32 v10, v10
	v_rcp_f32_e32 v12, v12
	v_add_u32_e32 v4, 28, v4
	v_mul_f32_e32 v5, v10, v5
	v_mul_f32_e32 v10, v12, v11
	v_mul_f32_e32 v5, v5, v13
	v_mul_f32_e32 v6, v10, v6
	v_cvt_pk_bf16_f32 v6, v5, v6
	v_lshlrev_b32_e32 v5, 16, v71
	v_and_b32_e32 v11, 0xffff0000, v71
	v_mul_f32_e32 v10, 0xbfb8aa3b, v5
	v_mul_f32_e32 v12, 0xbfb8aa3b, v11
	v_exp_f32_e32 v10, v10
	v_exp_f32_e32 v12, v12
	v_lshlrev_b32_e32 v13, 16, v7
	v_and_b32_e32 v7, 0xffff0000, v7
	v_add_f32_e32 v10, 1.0, v10
	v_add_f32_e32 v12, 1.0, v12
	v_rcp_f32_e32 v10, v10
	v_rcp_f32_e32 v12, v12
	v_mul_f32_e32 v5, v10, v5
	v_mul_f32_e32 v10, v12, v11
	v_mul_f32_e32 v5, v5, v13
	v_mul_f32_e32 v7, v10, v7
	v_cvt_pk_bf16_f32 v7, v5, v7
	v_lshlrev_b32_e32 v5, 16, v72
	v_and_b32_e32 v11, 0xffff0000, v72
	v_mul_f32_e32 v10, 0xbfb8aa3b, v5
	v_mul_f32_e32 v12, 0xbfb8aa3b, v11
	v_exp_f32_e32 v10, v10
	v_exp_f32_e32 v12, v12
	v_lshlrev_b32_e32 v13, 16, v8
	v_and_b32_e32 v8, 0xffff0000, v8
	v_add_f32_e32 v10, 1.0, v10
	v_add_f32_e32 v12, 1.0, v12
	v_rcp_f32_e32 v10, v10
	v_rcp_f32_e32 v12, v12
	v_mul_f32_e32 v5, v10, v5
	v_mul_f32_e32 v10, v12, v11
	v_mul_f32_e32 v5, v5, v13
	v_mul_f32_e32 v8, v10, v8
	v_cvt_pk_bf16_f32 v8, v5, v8
	v_lshlrev_b32_e32 v5, 16, v73
	v_and_b32_e32 v11, 0xffff0000, v73
	v_mul_f32_e32 v10, 0xbfb8aa3b, v5
	v_mul_f32_e32 v12, 0xbfb8aa3b, v11
	v_exp_f32_e32 v10, v10
	v_exp_f32_e32 v12, v12
	v_lshlrev_b32_e32 v13, 16, v9
	v_and_b32_e32 v9, 0xffff0000, v9
	v_add_f32_e32 v10, 1.0, v10
	v_add_f32_e32 v12, 1.0, v12
	v_rcp_f32_e32 v10, v10
	v_rcp_f32_e32 v12, v12
	v_mul_f32_e32 v5, v10, v5
	v_mul_f32_e32 v10, v12, v11
	v_mul_f32_e32 v9, v10, v9
	v_add_co_u32_e32 v10, vcc, s84, v2
	v_mul_f32_e32 v5, v5, v13
	s_nop 0
	v_addc_co_u32_e32 v11, vcc, 0, v3, vcc
	v_cvt_pk_bf16_f32 v9, v5, v9
	global_store_dwordx4 v[10:11], v[6:9], off
	v_and_b32_e32 v10, 0xffff0000, v66
	v_mul_f32_e32 v11, 0xbfb8aa3b, v10
	v_lshlrev_b32_e32 v8, 16, v66
	v_mul_f32_e32 v9, 0xbfb8aa3b, v8
	v_lshlrev_b32_e32 v5, 8, v4
	v_xor_b32_e32 v4, v4, v82
	v_exp_f32_e32 v9, v9
	v_exp_f32_e32 v11, v11
	v_lshlrev_b32_e32 v4, 4, v4
	v_and_b32_e32 v4, 0xf0, v4
	v_add3_u32 v4, s18, v5, v4
	ds_read_b128 v[4:7], v4
	v_add_f32_e32 v9, 1.0, v9
	v_add_f32_e32 v11, 1.0, v11
	v_rcp_f32_e32 v9, v9
	v_rcp_f32_e32 v11, v11
	s_waitcnt lgkmcnt(0)
	v_lshlrev_b32_e32 v12, 16, v4
	v_and_b32_e32 v4, 0xffff0000, v4
	v_mul_f32_e32 v8, v9, v8
	v_mul_f32_e32 v9, v11, v10
	v_mul_f32_e32 v8, v8, v12
	v_mul_f32_e32 v4, v9, v4
	v_cvt_pk_bf16_f32 v4, v8, v4
	v_lshlrev_b32_e32 v8, 16, v67
	v_and_b32_e32 v10, 0xffff0000, v67
	v_mul_f32_e32 v9, 0xbfb8aa3b, v8
	v_mul_f32_e32 v11, 0xbfb8aa3b, v10
	v_exp_f32_e32 v9, v9
	v_exp_f32_e32 v11, v11
	v_lshlrev_b32_e32 v12, 16, v5
	v_and_b32_e32 v5, 0xffff0000, v5
	v_add_f32_e32 v9, 1.0, v9
	v_add_f32_e32 v11, 1.0, v11
	v_rcp_f32_e32 v9, v9
	v_rcp_f32_e32 v11, v11
	v_add_co_u32_e32 v2, vcc, 0x1c000, v2
	v_mul_f32_e32 v8, v9, v8
	v_mul_f32_e32 v9, v11, v10
	v_mul_f32_e32 v8, v8, v12
	v_mul_f32_e32 v5, v9, v5
	v_cvt_pk_bf16_f32 v5, v8, v5
	v_lshlrev_b32_e32 v8, 16, v68
	v_and_b32_e32 v10, 0xffff0000, v68
	v_mul_f32_e32 v9, 0xbfb8aa3b, v8
	v_mul_f32_e32 v11, 0xbfb8aa3b, v10
	v_exp_f32_e32 v9, v9
	v_exp_f32_e32 v11, v11
	v_lshlrev_b32_e32 v12, 16, v6
	v_and_b32_e32 v6, 0xffff0000, v6
	v_add_f32_e32 v9, 1.0, v9
	v_add_f32_e32 v11, 1.0, v11
	v_rcp_f32_e32 v9, v9
	v_rcp_f32_e32 v11, v11
	v_addc_co_u32_e32 v3, vcc, 0, v3, vcc
	v_mul_f32_e32 v8, v9, v8
	v_mul_f32_e32 v9, v11, v10
	v_mul_f32_e32 v8, v8, v12
	v_mul_f32_e32 v6, v9, v6
	v_cvt_pk_bf16_f32 v6, v8, v6
	v_lshlrev_b32_e32 v8, 16, v69
	v_and_b32_e32 v10, 0xffff0000, v69
	v_mul_f32_e32 v9, 0xbfb8aa3b, v8
	v_mul_f32_e32 v11, 0xbfb8aa3b, v10
	v_exp_f32_e32 v9, v9
	v_exp_f32_e32 v11, v11
	v_lshlrev_b32_e32 v12, 16, v7
	v_and_b32_e32 v7, 0xffff0000, v7
	v_add_f32_e32 v9, 1.0, v9
	v_add_f32_e32 v11, 1.0, v11
	v_rcp_f32_e32 v9, v9
	v_rcp_f32_e32 v11, v11
	v_mul_f32_e32 v8, v9, v8
	v_mul_f32_e32 v9, v11, v10
	v_mul_f32_e32 v7, v9, v7
	v_mul_f32_e32 v8, v8, v12
	v_cvt_pk_bf16_f32 v7, v8, v7
	global_store_dwordx4 v[2:3], v[4:7], off
	v_mov_b32_e32 v2, s44
	ds_read_b32 v2, v2
	s_andn2_b64 vcc, exec, s[16:17]
	s_mov_b32 s22, s30
	s_waitcnt lgkmcnt(0)
	v_readfirstlane_b32 s4, v2
	s_mov_b32 s30, s4
	s_and_b32 s95, s30, 3
	s_lshr_b32 s96, s30, 2
	s_mul_i32 s97, s96, 0x889
	s_lshr_b32 s97, s97, 16
	s_mul_i32 s69, s97, 30
	s_sub_i32 s69, s96, s69
	s_add_i32 s69, s69, 1
	s_lshl_b32 s97, s97, 7
	s_lshl_b32 s69, s69, 2
	s_or_b32 s97, s97, s69
	s_or_b32 s97, s97, s95
	s_sub_i32 s96, s30, 0x4b0
	s_lshr_b32 s69, s96, 2
	s_and_b32 s96, s69, 1
	s_mul_i32 s96, s96, 0x7c
	s_lshr_b32 s69, s69, 1
	s_lshl_b32 s69, s69, 7
	s_or_b32 s69, s69, s96
	s_or_b32 s69, s69, s95
	s_cmp_lt_u32 s30, 0x4b0
	s_cselect_b32 s97, s97, s69
	s_cmp_lt_u32 s30, 0x500
	s_cselect_b32 s30, s97, s30
	s_cbranch_vccz .LBB0_500

; #define LAS __attribute__((address_space(3)))
; DI void phase_attn(const Params& P, int l, LAS unsigned char* lds) {
;     ...
;     unsigned* qctr = (unsigned*)(P.ws + WS_CTL) + 3584 + 64 * l;
;     volatile LAS int* slot = (volatile LAS int*)(lds + AT_END);
;     if (tid == 0) { const int a0 = (int)__hip_atomic_fetch_add(qctr, 1u, __ATOMIC_RELAXED, __HIP_MEMORY_SCOPE_AGENT); const int a1 = (int)__hip_atomic_fetch_add(qctr, 1u, __ATOMIC_RELAXED, __HIP_MEMORY_SCOPE_AGENT); slot[0] = a0; slot[1] = a1; }
;     __syncthreads();
;     int item = slot[0], inext = slot[1]; int pend = AT_NITEM;
;     if (item >= AT_NITEM) return;
;     int e = 0;
;     { const int n0 = (item >> 2) & 31; __syncthreads(); AT_ISSUE(item, n0 == 0 ? 1 : 0, 0); }
;     bf16x8 qr[8];
;     ...
;     AT_QLOAD(item);
.LBB0_1031:
	s_or_b64 exec, exec, s[4:5]
	s_add_i32 s4, 0, 0x24000
	v_mov_b32_e32 v3, s4
	s_add_i32 s4, 0, 0x24004
	s_waitcnt lgkmcnt(0)
	s_barrier
	ds_read_b32 v3, v3
	v_mov_b32_e32 v5, s4
	ds_read_b32 v5, v5
	s_movk_i32 s4, 0x4ff
	s_mov_b32 s5, 0
	s_waitcnt lgkmcnt(1)
	v_cmp_lt_i32_e32 vcc, s4, v3
	v_readfirstlane_b32 s26, v3
	s_waitcnt lgkmcnt(0)
	v_readfirstlane_b32 s36, v5
	s_cbranch_vccnz .LBB0_1063
	s_and_b32 s95, s26, 3
	s_lshr_b32 s96, s26, 2
	s_mul_i32 s97, s96, 0x889
	s_lshr_b32 s97, s97, 16
	s_mul_i32 s69, s97, 30
	s_sub_i32 s69, s96, s69
	s_add_i32 s69, s69, 1
	s_lshl_b32 s97, s97, 7
	s_lshl_b32 s69, s69, 2
	s_or_b32 s97, s97, s69
	s_or_b32 s97, s97, s95
	s_sub_i32 s96, s26, 0x4b0
	s_lshr_b32 s69, s96, 2
	s_and_b32 s96, s69, 1
	s_mul_i32 s96, s96, 0x7c
	s_lshr_b32 s69, s69, 1
	s_lshl_b32 s69, s69, 7
	s_or_b32 s69, s69, s96
	s_or_b32 s69, s69, s95
	s_cmp_lt_u32 s26, 0x4b0
	s_cselect_b32 s97, s97, s69
	s_cmp_lt_u32 s26, 0x500
	s_cselect_b32 s26, s97, s26
	s_and_b32 s95, s36, 3
	s_lshr_b32 s96, s36, 2
	s_mul_i32 s97, s96, 0x889
	s_lshr_b32 s97, s97, 16
	s_mul_i32 s69, s97, 30
	s_sub_i32 s69, s96, s69
	s_add_i32 s69, s69, 1
	s_lshl_b32 s97, s97, 7
	s_lshl_b32 s69, s69, 2
	s_or_b32 s97, s97, s69
	s_or_b32 s97, s97, s95
	s_sub_i32 s96, s36, 0x4b0
	s_lshr_b32 s69, s96, 2
	s_and_b32 s96, s69, 1
	s_mul_i32 s96, s96, 0x7c
	s_lshr_b32 s69, s69, 1
	s_lshl_b32 s69, s69, 7
	s_or_b32 s69, s69, s96
	s_or_b32 s69, s69, s95
	s_cmp_lt_u32 s36, 0x4b0
	s_cselect_b32 s97, s97, s69
	s_cmp_lt_u32 s36, 0x500
	s_cselect_b32 s36, s97, s36
	s_lshl_b32 s18, s13, 13
	s_lshl_b32 s4, s14, 14
	s_and_b32 s19, s18, 0x2000
	s_add_u32 s6, s50, s6
	s_addc_u32 s7, s51, s7
	s_add_u32 s8, s50, 0x3c40000
	s_addc_u32 s9, s51, 0
	s_add_u32 s10, s50, 0x1f940000
	s_addc_u32 s11, s51, 0
	s_ashr_i32 s14, s26, 7
	s_bfe_u32 s22, s26, 0x10001
	s_ashr_i32 s15, s14, 31
	s_add_i32 s20, 0, 0x8000
	s_bfe_u32 s21, s26, 0x50002
	s_mul_i32 s16, s22, 0xa000
	s_lshl_b64 s[14:15], s[14:15], 12
	s_add_u32 s23, s14, s16
	s_addc_u32 s24, s15, 0
	v_sub_co_u32_e64 v3, s[16:17], s21, 1
	s_nop 0
	v_readfirstlane_b32 s25, v3
	s_cmp_lg_u64 s[16:17], 0
	s_addc_u32 s16, s25, 0
	s_lshl_b32 s16, s16, 7
	s_ashr_i32 s17, s16, 31
	s_add_u32 s16, s23, s16
	s_addc_u32 s17, s24, s17
	s_lshl_b64 s[16:17], s[16:17], 8
	v_mov_b32_e32 v159, 0
	s_add_u32 s16, s6, s16
	s_addc_u32 s17, s7, s17
	s_add_i32 s37, s19, 0
	v_mov_b32_e32 v149, v159
	s_add_i32 s37, s37, s4
	v_lshlrev_b64 v[8:9], 1, v[148:149]
	v_lshl_add_u64 v[10:11], s[16:17], 0, v[8:9]
	s_mov_b32 m0, s37
	v_mov_b32_e32 v151, v159
	s_barrier
	global_load_lds_dwordx4 v[10:11], off
	v_lshlrev_b64 v[10:11], 1, v[150:151]
	v_lshl_add_u64 v[12:13], s[16:17], 0, v[10:11]
	s_add_i32 m0, s37, 0x400
	v_mov_b32_e32 v153, v159
	global_load_lds_dwordx4 v[12:13], off
	v_lshlrev_b64 v[12:13], 1, v[152:153]
	v_lshl_add_u64 v[14:15], s[16:17], 0, v[12:13]
	s_add_i32 m0, s37, 0x800
	v_mov_b32_e32 v155, v159
	global_load_lds_dwordx4 v[14:15], off
	v_lshlrev_b64 v[14:15], 1, v[154:155]
	v_lshl_add_u64 v[16:17], s[16:17], 0, v[14:15]
	s_add_i32 m0, s37, 0xc00
	v_mov_b32_e32 v157, v159
	global_load_lds_dwordx4 v[16:17], off
	v_lshlrev_b64 v[16:17], 1, v[156:157]
	v_lshl_add_u64 v[18:19], s[16:17], 0, v[16:17]
	s_add_i32 m0, s37, 0x1000
	v_mov_b32_e32 v3, v159
	global_load_lds_dwordx4 v[18:19], off
	v_lshlrev_b64 v[18:19], 1, v[158:159]
	v_lshl_add_u64 v[20:21], s[16:17], 0, v[18:19]
	s_add_i32 m0, s37, 0x1400
	v_lshlrev_b64 v[2:3], 1, v[2:3]
	v_mov_b32_e32 v5, v159
	global_load_lds_dwordx4 v[20:21], off
	v_lshl_add_u64 v[20:21], s[16:17], 0, v[2:3]
	s_add_i32 m0, s37, 0x1800
	v_lshlrev_b64 v[4:5], 1, v[4:5]
	s_lshr_b32 s39, s12, 8
	s_lshl_b32 s4, s13, 5
	global_load_lds_dwordx4 v[20:21], off
	v_lshl_add_u64 v[20:21], s[16:17], 0, v[4:5]
	s_lshl_b32 s16, s39, 6
	s_and_b32 s17, s4, 0x60
	s_xor_b32 s40, s17, s16
	s_lshl_b32 s4, s21, 7
	s_add_i32 m0, s37, 0x1c00
	s_add_i32 s41, s18, 0
	s_add_i32 s4, s4, s40
	s_add_u32 s4, s14, s4
	s_movk_i32 s38, 0x1400
	global_load_lds_dwordx4 v[20:21], off
	v_or_b32_e32 v7, s4, v1
	v_mov_b64_e32 v[20:21], s[8:9]
	v_mad_u64_u32 v[20:21], s[12:13], v7, s38, v[20:21]
	s_addc_u32 s14, s15, 0
	s_lshl_b32 s12, s26, 1
	s_and_b32 s12, s12, 2
	s_add_i32 s12, s12, s39
	v_mov_b32_e32 v204, 0x1400
	s_lshl_b32 s4, s22, 9
	s_lshl_b32 s12, s12, 7
	v_mad_i32_i24 v21, s14, v204, v21
	s_add_i32 s4, s12, s4
	v_lshl_add_u64 v[20:21], s[4:5], 1, v[20:21]
	v_mov_b32_e32 v147, v159
	v_lshl_add_u64 v[20:21], v[20:21], 0, v[146:147]
	global_load_dwordx4 v[98:101], v[20:21], off offset:224 nt
	global_load_dwordx4 v[102:105], v[20:21], off offset:192 nt
	global_load_dwordx4 v[106:109], v[20:21], off offset:160 nt
	global_load_dwordx4 v[110:113], v[20:21], off offset:128 nt
	global_load_dwordx4 v[114:117], v[20:21], off offset:96 nt
	global_load_dwordx4 v[118:121], v[20:21], off offset:64 nt
	global_load_dwordx4 v[122:125], v[20:21], off offset:32 nt
	global_load_dwordx4 v[126:129], v[20:21], off nt
	v_lshl_add_u64 v[168:169], s[6:7], 0, v[2:3]
	v_mov_b32_e32 v3, s16
	v_bitop3_b32 v3, s17, v1, v3 bitop3:0xde
	v_lshlrev_b32_e32 v7, 4, v137
	v_lshl_or_b32 v2, s39, 11, v146
	v_lshlrev_b32_e32 v3, 2, v3
	v_and_b32_e32 v21, 0xc0, v7
	v_lshlrev_b32_e32 v22, 1, v137
	s_movk_i32 s43, 0x70
	v_sub_u32_e32 v2, v2, v3
	s_movk_i32 s42, 0xc0
	v_lshlrev_b32_e32 v160, 3, v202
	v_and_b32_e32 v20, 0x78, v6
	v_and_b32_e32 v6, 0x118, v6
	v_and_b32_e32 v23, 0x70, v7
	v_bitop3_b32 v202, v146, v7, s43 bitop3:0x78
	s_movk_i32 s44, 0x60
	s_movk_i32 s45, 0x80
	s_movk_i32 s52, 0xa0
	s_movk_i32 s53, 0xe0
	v_and_or_b32 v7, v22, 32, v21
	v_add_u32_e32 v213, 0, v2
	v_mbcnt_lo_u32_b32 v2, -1, 0
	v_lshrrev_b32_e32 v162, 4, v161
	v_bitop3_b32 v205, v146, v23, 32 bitop3:0x36
	v_bitop3_b32 v206, v146, v23, 64 bitop3:0x36
	v_bitop3_b32 v207, v146, v23, s44 bitop3:0x36
	v_bitop3_b32 v208, v146, v23, s45 bitop3:0x36
	v_bitop3_b32 v209, v146, v23, s52 bitop3:0x36
	v_bitop3_b32 v210, v146, v23, s42 bitop3:0x36
	v_bitop3_b32 v211, v146, v23, s53 bitop3:0x36
	s_mov_b32 s54, 0x8000
	v_add3_u32 v212, v6, s20, v7
	v_lshl_add_u64 v[164:165], s[6:7], 0, v[4:5]
	v_lshl_add_u64 v[166:167], s[6:7], 0, v[18:19]
	v_lshl_add_u64 v[170:171], s[6:7], 0, v[8:9]
	v_lshl_add_u64 v[172:173], s[6:7], 0, v[10:11]
	v_lshl_add_u64 v[174:175], s[6:7], 0, v[12:13]
	v_lshl_add_u64 v[176:177], s[6:7], 0, v[14:15]
	v_lshl_add_u64 v[178:179], s[6:7], 0, v[16:17]
	v_mov_b32_e32 v215, 0x500
	v_lshlrev_b32_e32 v158, 1, v20
	s_mov_b64 s[12:13], 0xc00
	s_mov_b64 s[14:15], 0x5c00
	s_mov_b64 s[16:17], 0xac00
	s_mov_b64 s[18:19], 0xfc00
	s_add_i32 s55, 0, 0x24008
	s_mov_b32 s56, 0x10000
	s_mov_b32 s57, 0xf149f2ca
	s_mov_b32 s58, 0x41000000
	s_movk_i32 s59, 0x4000
	s_mov_b32 s74, 0x14000
	s_movk_i32 s75, 0x50
	s_movk_i32 s76, 0x90
	s_movk_i32 s77, 0xb0
	s_movk_i32 s78, 0xd0
	s_movk_i32 s79, 0xf0
	s_mov_b32 s80, 0xc000
	s_mov_b32 s81, 0x18000
	v_mbcnt_hi_u32_b32 v214, -1, v2
	s_mov_b32 s82, 0
	s_waitcnt vmcnt(0)
	s_branch .LBB0_1034
; #define LAS __attribute__((address_space(3)))
; DI unsigned cvt_pk_bf16(float lo, float hi) { unsigned r; asm volatile("v_cvt_pk_bf16_f32 %0, %1, %2" : "=v"(r) : "v"(lo), "v"(hi)); return r; }
; DI void phase_attn(const Params& P, int l, LAS unsigned char* lds) {
;     ...
;         if (inext < AT_NITEM) AT_QLOAD(inext);
;         const float rl = __builtin_amdgcn_rcpf(l_run);
; #pragma unroll
;         for (int it = 4; it < 8; ++it) zz[it] = __builtin_nontemporal_load((const u32x4*)(zp + (size_t)it * 4 * 2560));
;         asm volatile("s_waitcnt lgkmcnt(0)" ::: "memory"); __builtin_amdgcn_s_barrier(); asm volatile("" ::: "memory");
;         { LAS unsigned char* stg = lds + ((e & 1) ^ 1) * AT_BUF + wid * 8192; int rsw = r32 & 15, lsw = lane; asm volatile("" : "+v"(rsw), "+v"(lsw));
; #pragma unroll
;           for (int d0 = 0; d0 < 4; ++d0)
; #pragma unroll
;               for (int a4 = 0; a4 < 4; ++a4) { u32x2 w; w.x = cvt_pk_bf16(o[d0][a4 * 4 + 0] * rl, o[d0][a4 * 4 + 1] * rl); w.y = cvt_pk_bf16(o[d0][a4 * 4 + 2] * rl, o[d0][a4 * 4 + 3] * rl);
;                   *(LAS u32x2*)(stg + r32 * 256 + (((d0 * 4 + a4) ^ rsw) << 4) + hi * 8) = w; }
.LBB0_1033:
	v_add_co_u32_e32 v66, vcc, 0x14000, v180
	v_rcp_f32_e32 v83, v219
	s_nop 0
	v_addc_co_u32_e32 v67, vcc, 0, v181, vcc
	v_add_co_u32_e32 v68, vcc, 0x19000, v180
	s_add_i32 s82, s82, s85
	s_nop 0
	v_addc_co_u32_e32 v69, vcc, 0, v181, vcc
	global_load_dwordx4 v[78:81], v[66:67], off nt
	global_load_dwordx4 v[74:77], v[68:69], off nt
	v_add_co_u32_e32 v66, vcc, 0x1e000, v180
	s_not_b32 s4, s82
	s_nop 0
	v_addc_co_u32_e32 v67, vcc, 0, v181, vcc
	v_add_co_u32_e32 v68, vcc, 0x23000, v180
	s_lshl_b32 s4, s4, 16
	s_nop 0
	v_addc_co_u32_e32 v69, vcc, 0, v181, vcc
	s_and_b32 s4, s4, 0x10000
	v_mov_b32_e32 v82, v161
	v_mov_b32_e32 v84, v163
	v_mul_f32_e32 v50, v50, v83
	v_mul_f32_e32 v51, v51, v83
	global_load_dwordx4 v[70:73], v[66:67], off nt
	s_nop 0
	global_load_dwordx4 v[66:69], v[68:69], off nt
	s_waitcnt lgkmcnt(0)
	s_barrier
	s_add_i32 s22, s41, s4
	v_cvt_pk_bf16_f32 v50, v50, v51
	v_mul_f32_e32 v51, v52, v83
	v_mul_f32_e32 v52, v53, v83
	v_add3_u32 v85, s22, v201, v160
	v_cvt_pk_bf16_f32 v51, v51, v52
	v_lshlrev_b32_e32 v52, 4, v84
	v_add_u32_e32 v53, v85, v52
	ds_write_b64 v53, v[50:51]
	v_mul_f32_e32 v50, v54, v83
	v_mul_f32_e32 v51, v55, v83
	v_cvt_pk_bf16_f32 v50, v50, v51
	v_mul_f32_e32 v51, v56, v83
	v_mul_f32_e32 v53, v57, v83
	v_cvt_pk_bf16_f32 v51, v51, v53
	v_xad_u32 v53, v52, 16, v85
	ds_write_b64 v53, v[50:51]
	v_mul_f32_e32 v50, v58, v83
	v_mul_f32_e32 v51, v59, v83
	v_cvt_pk_bf16_f32 v50, v50, v51
	v_mul_f32_e32 v51, v60, v83
	v_mul_f32_e32 v53, v61, v83
	v_cvt_pk_bf16_f32 v51, v51, v53
	v_xad_u32 v53, v52, 32, v85
	ds_write_b64 v53, v[50:51]
	v_mul_f32_e32 v50, v62, v83
	v_mul_f32_e32 v51, v63, v83
	v_cvt_pk_bf16_f32 v50, v50, v51
	v_mul_f32_e32 v51, v64, v83
	v_mul_f32_e32 v53, v65, v83
	v_cvt_pk_bf16_f32 v51, v51, v53
	v_xad_u32 v53, v52, 48, v85
	v_mul_f32_e32 v34, v34, v83
	v_mul_f32_e32 v35, v35, v83
	ds_write_b64 v53, v[50:51]
	v_cvt_pk_bf16_f32 v34, v34, v35
	v_mul_f32_e32 v35, v36, v83
	v_mul_f32_e32 v36, v37, v83
	v_cvt_pk_bf16_f32 v35, v35, v36
	v_xad_u32 v36, v52, 64, v85
	ds_write_b64 v36, v[34:35]
	v_mul_f32_e32 v34, v38, v83
	v_mul_f32_e32 v35, v39, v83
	v_cvt_pk_bf16_f32 v34, v34, v35
	v_mul_f32_e32 v35, v40, v83
	v_mul_f32_e32 v36, v41, v83
	v_cvt_pk_bf16_f32 v35, v35, v36
	v_xad_u32 v36, v52, s75, v85
	ds_write_b64 v36, v[34:35]
	v_mul_f32_e32 v34, v42, v83
	v_mul_f32_e32 v35, v43, v83
	v_cvt_pk_bf16_f32 v34, v34, v35
	v_mul_f32_e32 v35, v44, v83
	v_mul_f32_e32 v36, v45, v83
	v_cvt_pk_bf16_f32 v35, v35, v36
	v_xad_u32 v36, v52, s44, v85
	ds_write_b64 v36, v[34:35]
	v_mul_f32_e32 v34, v46, v83
	v_mul_f32_e32 v35, v47, v83
	v_cvt_pk_bf16_f32 v34, v34, v35
	v_mul_f32_e32 v35, v48, v83
	v_mul_f32_e32 v36, v49, v83
	v_cvt_pk_bf16_f32 v35, v35, v36
	v_xad_u32 v36, v52, s43, v85
	v_mul_f32_e32 v18, v18, v83
	v_mul_f32_e32 v19, v19, v83
	ds_write_b64 v36, v[34:35]
	v_cvt_pk_bf16_f32 v18, v18, v19
	v_mul_f32_e32 v19, v20, v83
	v_mul_f32_e32 v20, v21, v83
	v_cvt_pk_bf16_f32 v19, v19, v20
	v_xad_u32 v20, v52, s45, v85
	ds_write_b64 v20, v[18:19]
	v_mul_f32_e32 v18, v22, v83
	v_mul_f32_e32 v19, v23, v83
	v_cvt_pk_bf16_f32 v18, v18, v19
	v_mul_f32_e32 v19, v24, v83
	v_mul_f32_e32 v20, v25, v83
	v_cvt_pk_bf16_f32 v19, v19, v20
	v_xad_u32 v20, v52, s76, v85
	ds_write_b64 v20, v[18:19]
	v_mul_f32_e32 v18, v26, v83
	v_mul_f32_e32 v19, v27, v83
	v_cvt_pk_bf16_f32 v18, v18, v19
	v_mul_f32_e32 v19, v28, v83
	v_mul_f32_e32 v20, v29, v83
	v_cvt_pk_bf16_f32 v19, v19, v20
	v_xad_u32 v20, v52, s52, v85
	ds_write_b64 v20, v[18:19]
	v_mul_f32_e32 v18, v30, v83
	v_mul_f32_e32 v19, v31, v83
	v_cvt_pk_bf16_f32 v18, v18, v19
	v_mul_f32_e32 v19, v32, v83
	v_mul_f32_e32 v20, v33, v83
	v_cvt_pk_bf16_f32 v19, v19, v20
	v_xad_u32 v20, v52, s77, v85
	v_mul_f32_e32 v2, v2, v83
	v_mul_f32_e32 v3, v3, v83
	ds_write_b64 v20, v[18:19]
	v_cvt_pk_bf16_f32 v2, v2, v3
	v_mul_f32_e32 v3, v4, v83
	v_mul_f32_e32 v4, v5, v83
	v_cvt_pk_bf16_f32 v3, v3, v4
	v_xad_u32 v4, v52, s42, v85
	ds_write_b64 v4, v[2:3]
	v_mul_f32_e32 v2, v6, v83
	v_mul_f32_e32 v3, v7, v83
	v_cvt_pk_bf16_f32 v2, v2, v3
	v_mul_f32_e32 v3, v8, v83
	v_mul_f32_e32 v4, v9, v83
	v_cvt_pk_bf16_f32 v3, v3, v4
	v_xad_u32 v4, v52, s78, v85
	ds_write_b64 v4, v[2:3]
	v_mul_f32_e32 v2, v10, v83
	v_mul_f32_e32 v3, v11, v83
	v_cvt_pk_bf16_f32 v2, v2, v3
	v_mul_f32_e32 v3, v12, v83
	v_mul_f32_e32 v4, v13, v83
	v_cvt_pk_bf16_f32 v3, v3, v4
	v_xad_u32 v4, v52, s53, v85
	ds_write_b64 v4, v[2:3]
	v_mul_f32_e32 v2, v14, v83
	v_mul_f32_e32 v3, v15, v83
	v_cvt_pk_bf16_f32 v2, v2, v3
	v_mul_f32_e32 v3, v16, v83
	v_mul_f32_e32 v4, v17, v83
	v_cvt_pk_bf16_f32 v3, v3, v4
	v_xad_u32 v4, v52, s79, v85
	s_waitcnt vmcnt(0)
	v_lshlrev_b32_e32 v10, 16, v142
	v_and_b32_e32 v12, 0xffff0000, v142
	ds_write_b64 v4, v[2:3]
	v_ashrrev_i32_e32 v4, 4, v82
	v_mul_f32_e32 v11, 0xbfb8aa3b, v10
	v_mul_f32_e32 v13, 0xbfb8aa3b, v12
	v_xor_b32_e32 v6, v4, v82
	v_exp_f32_e32 v11, v11
	v_exp_f32_e32 v13, v13
	v_lshlrev_b32_e32 v6, 4, v6
	v_lshlrev_b32_e32 v5, 8, v4
	v_and_b32_e32 v6, 0xf0, v6
	s_waitcnt lgkmcnt(0)
	v_add3_u32 v5, s22, v5, v6
	ds_read_b128 v[6:9], v5
	v_add_f32_e32 v11, 1.0, v11
	v_add_f32_e32 v13, 1.0, v13
	v_rcp_f32_e32 v11, v11
	v_rcp_f32_e32 v13, v13
	s_waitcnt lgkmcnt(0)
; #define LAS __attribute__((address_space(3)))
; DI unsigned cvt_pk_bf16(float lo, float hi) { unsigned r; asm volatile("v_cvt_pk_bf16_f32 %0, %1, %2" : "=v"(r) : "v"(lo), "v"(hi)); return r; }
; DI float bflo(unsigned w) { return __uint_as_float(w << 16); }
; DI float bfhi(unsigned w) { return __uint_as_float(w & 0xffff0000u); }
; DI float silu_fast(float z) { return z * __builtin_amdgcn_rcpf(1.0f + __builtin_amdgcn_exp2f(-z * LOG2E)); }
; DI void phase_attn(const Params& P, int l, LAS unsigned char* lds) {
;     ...
;           bf16_t* op = MI + (tokw + (lane >> 4)) * DM + g * 128 + (lane & 15) * 8;
; #pragma unroll
;           for (int it = 0; it < 8; ++it) { const int row = it * 4 + (lsw >> 4);
;               const u32x4 ov = *(const LAS u32x4*)(stg + row * 256 + (((lsw & 15) ^ (row & 15)) << 4)); const u32x4 z = zz[it]; u32x4 w;
; #pragma unroll
;               for (int q = 0; q < 4; ++q) w[q] = cvt_pk_bf16(bflo(ov[q]) * silu_fast(bflo(z[q])), bfhi(ov[q]) * silu_fast(bfhi(z[q])));
;               *(u32x4*)(op + (size_t)it * 4 * DM) = w; if (it & 1) __builtin_amdgcn_sched_barrier(0); } }
	v_lshlrev_b32_e32 v14, 16, v6
	v_and_b32_e32 v6, 0xffff0000, v6
	v_mul_f32_e32 v10, v11, v10
	v_mul_f32_e32 v11, v13, v12
	v_mul_f32_e32 v10, v10, v14
	v_mul_f32_e32 v6, v11, v6
	v_cvt_pk_bf16_f32 v6, v10, v6
	v_lshlrev_b32_e32 v10, 16, v143
	v_and_b32_e32 v12, 0xffff0000, v143
	v_mul_f32_e32 v11, 0xbfb8aa3b, v10
	v_mul_f32_e32 v13, 0xbfb8aa3b, v12
	v_exp_f32_e32 v11, v11
	v_exp_f32_e32 v13, v13
	v_lshlrev_b32_e32 v14, 16, v7
	v_and_b32_e32 v7, 0xffff0000, v7
	v_add_f32_e32 v11, 1.0, v11
	v_add_f32_e32 v13, 1.0, v13
	v_rcp_f32_e32 v11, v11
	v_rcp_f32_e32 v13, v13
	v_lshlrev_b64 v[2:3], 12, v[146:147]
	v_lshl_add_u64 v[2:3], s[10:11], 0, v[2:3]
	v_mul_f32_e32 v10, v11, v10
	v_mul_f32_e32 v11, v13, v12
	v_mul_f32_e32 v10, v10, v14
	v_mul_f32_e32 v7, v11, v7
	v_cvt_pk_bf16_f32 v7, v10, v7
	v_lshlrev_b32_e32 v10, 16, v144
	v_and_b32_e32 v12, 0xffff0000, v144
	v_mul_f32_e32 v11, 0xbfb8aa3b, v10
	v_mul_f32_e32 v13, 0xbfb8aa3b, v12
	v_exp_f32_e32 v11, v11
	v_exp_f32_e32 v13, v13
	v_lshlrev_b32_e32 v14, 16, v8
	v_and_b32_e32 v8, 0xffff0000, v8
	v_add_f32_e32 v11, 1.0, v11
	v_add_f32_e32 v13, 1.0, v13
	v_rcp_f32_e32 v11, v11
	v_rcp_f32_e32 v13, v13
	s_lshl_b32 s4, s83, 1
	v_lshl_add_u64 v[2:3], v[2:3], 0, s[4:5]
	v_mul_f32_e32 v10, v11, v10
	v_mul_f32_e32 v11, v13, v12
	v_mul_f32_e32 v10, v10, v14
	v_mul_f32_e32 v8, v11, v8
	v_cvt_pk_bf16_f32 v8, v10, v8
	v_lshlrev_b32_e32 v10, 16, v145
	v_and_b32_e32 v12, 0xffff0000, v145
	v_mul_f32_e32 v11, 0xbfb8aa3b, v10
	v_mul_f32_e32 v13, 0xbfb8aa3b, v12
	v_exp_f32_e32 v11, v11
	v_exp_f32_e32 v13, v13
	v_lshlrev_b32_e32 v14, 16, v9
	v_and_b32_e32 v9, 0xffff0000, v9
	v_add_f32_e32 v11, 1.0, v11
	v_add_f32_e32 v13, 1.0, v13
	v_rcp_f32_e32 v11, v11
	v_rcp_f32_e32 v13, v13
	v_lshl_add_u64 v[2:3], v[2:3], 0, v[158:159]
	v_mul_f32_e32 v10, v11, v10
	v_mul_f32_e32 v11, v13, v12
	v_mul_f32_e32 v10, v10, v14
	v_mul_f32_e32 v9, v11, v9
	v_cvt_pk_bf16_f32 v9, v10, v9
	v_lshlrev_b32_e32 v10, 16, v138
	v_and_b32_e32 v12, 0xffff0000, v138
	global_store_dwordx4 v[2:3], v[6:9], off
	v_mul_f32_e32 v11, 0xbfb8aa3b, v10
	v_mul_f32_e32 v13, 0xbfb8aa3b, v12
	v_add_u32_e32 v6, 4, v4
	v_lshlrev_b32_e32 v7, 8, v6
	v_xor_b32_e32 v6, v6, v82
	v_exp_f32_e32 v11, v11
	v_exp_f32_e32 v13, v13
	v_lshlrev_b32_e32 v6, 4, v6
	v_and_b32_e32 v6, 0xf0, v6
	v_add3_u32 v6, s22, v7, v6
	ds_read_b128 v[6:9], v6
	v_add_f32_e32 v11, 1.0, v11
	v_add_f32_e32 v13, 1.0, v13
	v_rcp_f32_e32 v11, v11
	v_rcp_f32_e32 v13, v13
	s_waitcnt lgkmcnt(0)
	v_lshlrev_b32_e32 v14, 16, v6
	v_and_b32_e32 v6, 0xffff0000, v6
	v_mul_f32_e32 v10, v11, v10
	v_mul_f32_e32 v11, v13, v12
	v_mul_f32_e32 v10, v10, v14
	v_mul_f32_e32 v6, v11, v6
	v_cvt_pk_bf16_f32 v6, v10, v6
	v_lshlrev_b32_e32 v10, 16, v139
	v_and_b32_e32 v12, 0xffff0000, v139
	v_mul_f32_e32 v11, 0xbfb8aa3b, v10
	v_mul_f32_e32 v13, 0xbfb8aa3b, v12
	v_exp_f32_e32 v11, v11
	v_exp_f32_e32 v13, v13
	v_lshlrev_b32_e32 v14, 16, v7
	v_and_b32_e32 v7, 0xffff0000, v7
	v_add_f32_e32 v11, 1.0, v11
	v_add_f32_e32 v13, 1.0, v13
	v_rcp_f32_e32 v11, v11
	v_rcp_f32_e32 v13, v13
	v_mul_f32_e32 v10, v11, v10
	v_mul_f32_e32 v11, v13, v12
	v_mul_f32_e32 v10, v10, v14
	v_mul_f32_e32 v7, v11, v7
	v_cvt_pk_bf16_f32 v7, v10, v7
	v_lshlrev_b32_e32 v10, 16, v140
	v_and_b32_e32 v12, 0xffff0000, v140
	v_mul_f32_e32 v11, 0xbfb8aa3b, v10
	v_mul_f32_e32 v13, 0xbfb8aa3b, v12
	v_exp_f32_e32 v11, v11
	v_exp_f32_e32 v13, v13
	v_lshlrev_b32_e32 v14, 16, v8
	v_and_b32_e32 v8, 0xffff0000, v8
	v_add_f32_e32 v11, 1.0, v11
	v_add_f32_e32 v13, 1.0, v13
	v_rcp_f32_e32 v11, v11
	v_rcp_f32_e32 v13, v13
	v_mul_f32_e32 v10, v11, v10
	v_mul_f32_e32 v11, v13, v12
	v_mul_f32_e32 v10, v10, v14
	v_mul_f32_e32 v8, v11, v8
	v_cvt_pk_bf16_f32 v8, v10, v8
	v_lshlrev_b32_e32 v10, 16, v141
	v_and_b32_e32 v12, 0xffff0000, v141
	v_mul_f32_e32 v11, 0xbfb8aa3b, v10
	v_mul_f32_e32 v13, 0xbfb8aa3b, v12
	v_exp_f32_e32 v11, v11
	v_exp_f32_e32 v13, v13
	v_lshlrev_b32_e32 v14, 16, v9
	v_and_b32_e32 v9, 0xffff0000, v9
	v_add_f32_e32 v11, 1.0, v11
	v_add_f32_e32 v13, 1.0, v13
	v_rcp_f32_e32 v11, v11
	v_rcp_f32_e32 v13, v13
	v_mul_f32_e32 v10, v11, v10
	v_mul_f32_e32 v11, v13, v12
	v_mul_f32_e32 v10, v10, v14
	v_mul_f32_e32 v9, v11, v9
	v_cvt_pk_bf16_f32 v9, v10, v9
	v_add_co_u32_e32 v10, vcc, s59, v2
	s_nop 1
	v_addc_co_u32_e32 v11, vcc, 0, v3, vcc
	global_store_dwordx4 v[10:11], v[6:9], off
	v_lshlrev_b32_e32 v10, 16, v134
	v_and_b32_e32 v12, 0xffff0000, v134
	v_add_u32_e32 v6, 8, v4
	v_mul_f32_e32 v11, 0xbfb8aa3b, v10
	v_mul_f32_e32 v13, 0xbfb8aa3b, v12
	v_lshlrev_b32_e32 v7, 8, v6
	v_xor_b32_e32 v6, v6, v82
	v_exp_f32_e32 v11, v11
	v_exp_f32_e32 v13, v13
	v_lshlrev_b32_e32 v6, 4, v6
	v_and_b32_e32 v6, 0xf0, v6
	v_add3_u32 v6, s22, v7, v6
	ds_read_b128 v[6:9], v6
	v_add_f32_e32 v11, 1.0, v11
	v_add_f32_e32 v13, 1.0, v13
	v_rcp_f32_e32 v11, v11
	v_rcp_f32_e32 v13, v13
	s_waitcnt lgkmcnt(0)
; #define LAS __attribute__((address_space(3)))
; DI unsigned cvt_pk_bf16(float lo, float hi) { unsigned r; asm volatile("v_cvt_pk_bf16_f32 %0, %1, %2" : "=v"(r) : "v"(lo), "v"(hi)); return r; }
; DI float bflo(unsigned w) { return __uint_as_float(w << 16); }
; DI float bfhi(unsigned w) { return __uint_as_float(w & 0xffff0000u); }
; DI float silu_fast(float z) { return z * __builtin_amdgcn_rcpf(1.0f + __builtin_amdgcn_exp2f(-z * LOG2E)); }
; DI void phase_attn(const Params& P, int l, LAS unsigned char* lds) {
;     ...
;           bf16_t* op = MI + (tokw + (lane >> 4)) * DM + g * 128 + (lane & 15) * 8;
; #pragma unroll
;           for (int it = 0; it < 8; ++it) { const int row = it * 4 + (lsw >> 4);
;               const u32x4 ov = *(const LAS u32x4*)(stg + row * 256 + (((lsw & 15) ^ (row & 15)) << 4)); const u32x4 z = zz[it]; u32x4 w;
; #pragma unroll
;               for (int q = 0; q < 4; ++q) w[q] = cvt_pk_bf16(bflo(ov[q]) * silu_fast(bflo(z[q])), bfhi(ov[q]) * silu_fast(bfhi(z[q])));
;               *(u32x4*)(op + (size_t)it * 4 * DM) = w; if (it & 1) __builtin_amdgcn_sched_barrier(0); } }
	v_lshlrev_b32_e32 v14, 16, v6
	v_and_b32_e32 v6, 0xffff0000, v6
	v_mul_f32_e32 v10, v11, v10
	v_mul_f32_e32 v11, v13, v12
	v_mul_f32_e32 v10, v10, v14
	v_mul_f32_e32 v6, v11, v6
	v_cvt_pk_bf16_f32 v6, v10, v6
	v_lshlrev_b32_e32 v10, 16, v135
	v_and_b32_e32 v12, 0xffff0000, v135
	v_mul_f32_e32 v11, 0xbfb8aa3b, v10
	v_mul_f32_e32 v13, 0xbfb8aa3b, v12
	v_exp_f32_e32 v11, v11
	v_exp_f32_e32 v13, v13
	v_lshlrev_b32_e32 v14, 16, v7
	v_and_b32_e32 v7, 0xffff0000, v7
	v_add_f32_e32 v11, 1.0, v11
	v_add_f32_e32 v13, 1.0, v13
	v_rcp_f32_e32 v11, v11
	v_rcp_f32_e32 v13, v13
	v_mul_f32_e32 v10, v11, v10
	v_mul_f32_e32 v11, v13, v12
	v_mul_f32_e32 v10, v10, v14
	v_mul_f32_e32 v7, v11, v7
	v_cvt_pk_bf16_f32 v7, v10, v7
	v_lshlrev_b32_e32 v10, 16, v136
	v_and_b32_e32 v12, 0xffff0000, v136
	v_mul_f32_e32 v11, 0xbfb8aa3b, v10
	v_mul_f32_e32 v13, 0xbfb8aa3b, v12
	v_exp_f32_e32 v11, v11
	v_exp_f32_e32 v13, v13
	v_lshlrev_b32_e32 v14, 16, v8
	v_and_b32_e32 v8, 0xffff0000, v8
	v_add_f32_e32 v11, 1.0, v11
	v_add_f32_e32 v13, 1.0, v13
	v_rcp_f32_e32 v11, v11
	v_rcp_f32_e32 v13, v13
	v_mul_f32_e32 v10, v11, v10
	v_mul_f32_e32 v11, v13, v12
	v_mul_f32_e32 v10, v10, v14
	v_mul_f32_e32 v8, v11, v8
	v_cvt_pk_bf16_f32 v8, v10, v8
	v_lshlrev_b32_e32 v10, 16, v137
	v_and_b32_e32 v12, 0xffff0000, v137
	v_mul_f32_e32 v11, 0xbfb8aa3b, v10
	v_mul_f32_e32 v13, 0xbfb8aa3b, v12
	v_exp_f32_e32 v11, v11
	v_exp_f32_e32 v13, v13
	v_lshlrev_b32_e32 v14, 16, v9
	v_and_b32_e32 v9, 0xffff0000, v9
	v_add_f32_e32 v11, 1.0, v11
	v_add_f32_e32 v13, 1.0, v13
	v_rcp_f32_e32 v11, v11
	v_rcp_f32_e32 v13, v13
	v_mul_f32_e32 v10, v11, v10
	v_mul_f32_e32 v11, v13, v12
	v_mul_f32_e32 v10, v10, v14
	v_mul_f32_e32 v9, v11, v9
	v_cvt_pk_bf16_f32 v9, v10, v9
	v_add_co_u32_e32 v10, vcc, s54, v2
	v_and_b32_e32 v12, 0xffff0000, v130
	s_nop 0
	v_addc_co_u32_e32 v11, vcc, 0, v3, vcc
	global_store_dwordx4 v[10:11], v[6:9], off
	v_lshlrev_b32_e32 v10, 16, v130
	v_mul_f32_e32 v11, 0xbfb8aa3b, v10
	v_add_u32_e32 v6, 12, v4
	v_mul_f32_e32 v13, 0xbfb8aa3b, v12
	v_lshlrev_b32_e32 v7, 8, v6
	v_xor_b32_e32 v6, v6, v82
	v_exp_f32_e32 v11, v11
	v_exp_f32_e32 v13, v13
	v_lshlrev_b32_e32 v6, 4, v6
	v_and_b32_e32 v6, 0xf0, v6
	v_add3_u32 v6, s22, v7, v6
	ds_read_b128 v[6:9], v6
	v_add_f32_e32 v11, 1.0, v11
	v_add_f32_e32 v13, 1.0, v13
	v_rcp_f32_e32 v11, v11
	v_rcp_f32_e32 v13, v13
	s_waitcnt lgkmcnt(0)
	v_lshlrev_b32_e32 v14, 16, v6
	v_and_b32_e32 v6, 0xffff0000, v6
	v_mul_f32_e32 v10, v11, v10
	v_mul_f32_e32 v11, v13, v12
	v_mul_f32_e32 v10, v10, v14
	v_mul_f32_e32 v6, v11, v6
	v_cvt_pk_bf16_f32 v6, v10, v6
	v_lshlrev_b32_e32 v10, 16, v131
	v_and_b32_e32 v12, 0xffff0000, v131
	v_mul_f32_e32 v11, 0xbfb8aa3b, v10
	v_mul_f32_e32 v13, 0xbfb8aa3b, v12
	v_exp_f32_e32 v11, v11
	v_exp_f32_e32 v13, v13
	v_lshlrev_b32_e32 v14, 16, v7
	v_and_b32_e32 v7, 0xffff0000, v7
	v_add_f32_e32 v11, 1.0, v11
	v_add_f32_e32 v13, 1.0, v13
	v_rcp_f32_e32 v11, v11
	v_rcp_f32_e32 v13, v13
	v_mul_f32_e32 v10, v11, v10
	v_mul_f32_e32 v11, v13, v12
	v_mul_f32_e32 v10, v10, v14
	v_mul_f32_e32 v7, v11, v7
	v_cvt_pk_bf16_f32 v7, v10, v7
	v_lshlrev_b32_e32 v10, 16, v132
	v_and_b32_e32 v12, 0xffff0000, v132
	v_mul_f32_e32 v11, 0xbfb8aa3b, v10
	v_mul_f32_e32 v13, 0xbfb8aa3b, v12
	v_exp_f32_e32 v11, v11
	v_exp_f32_e32 v13, v13
	v_lshlrev_b32_e32 v14, 16, v8
	v_and_b32_e32 v8, 0xffff0000, v8
	v_add_f32_e32 v11, 1.0, v11
	v_add_f32_e32 v13, 1.0, v13
	v_rcp_f32_e32 v11, v11
	v_rcp_f32_e32 v13, v13
	v_mul_f32_e32 v10, v11, v10
	v_mul_f32_e32 v11, v13, v12
	v_mul_f32_e32 v10, v10, v14
	v_mul_f32_e32 v8, v11, v8
	v_cvt_pk_bf16_f32 v8, v10, v8
	v_lshlrev_b32_e32 v10, 16, v133
	v_and_b32_e32 v12, 0xffff0000, v133
	v_mul_f32_e32 v11, 0xbfb8aa3b, v10
	v_mul_f32_e32 v13, 0xbfb8aa3b, v12
	v_exp_f32_e32 v11, v11
	v_exp_f32_e32 v13, v13
	v_lshlrev_b32_e32 v14, 16, v9
	v_and_b32_e32 v9, 0xffff0000, v9
	v_add_f32_e32 v11, 1.0, v11
	v_add_f32_e32 v13, 1.0, v13
	v_rcp_f32_e32 v11, v11
	v_rcp_f32_e32 v13, v13
	v_mul_f32_e32 v10, v11, v10
	v_mul_f32_e32 v11, v13, v12
	v_mul_f32_e32 v10, v10, v14
	v_mul_f32_e32 v9, v11, v9
	v_cvt_pk_bf16_f32 v9, v10, v9
	v_add_co_u32_e32 v10, vcc, s80, v2
	s_nop 1
	v_addc_co_u32_e32 v11, vcc, 0, v3, vcc
	global_store_dwordx4 v[10:11], v[6:9], off
	ds_read_b128 v[6:9], v5 offset:4096
	v_lshlrev_b32_e32 v5, 16, v78
	v_and_b32_e32 v11, 0xffff0000, v78
	v_mul_f32_e32 v10, 0xbfb8aa3b, v5
	v_mul_f32_e32 v12, 0xbfb8aa3b, v11
	v_exp_f32_e32 v10, v10
	v_exp_f32_e32 v12, v12
	s_waitcnt lgkmcnt(0)
	v_lshlrev_b32_e32 v13, 16, v6
	v_and_b32_e32 v6, 0xffff0000, v6
	v_add_f32_e32 v10, 1.0, v10
	v_add_f32_e32 v12, 1.0, v12
	v_rcp_f32_e32 v10, v10
	v_rcp_f32_e32 v12, v12
	v_mul_f32_e32 v5, v10, v5
	v_mul_f32_e32 v10, v12, v11
	v_mul_f32_e32 v5, v5, v13
	v_mul_f32_e32 v6, v10, v6
	v_cvt_pk_bf16_f32 v6, v5, v6
	v_lshlrev_b32_e32 v5, 16, v79
	v_and_b32_e32 v11, 0xffff0000, v79
	v_mul_f32_e32 v10, 0xbfb8aa3b, v5
	v_mul_f32_e32 v12, 0xbfb8aa3b, v11
	v_exp_f32_e32 v10, v10
	v_exp_f32_e32 v12, v12
	v_lshlrev_b32_e32 v13, 16, v7
	v_and_b32_e32 v7, 0xffff0000, v7
	v_add_f32_e32 v10, 1.0, v10
	v_add_f32_e32 v12, 1.0, v12
	v_rcp_f32_e32 v10, v10
	v_rcp_f32_e32 v12, v12
	v_mul_f32_e32 v5, v10, v5
	v_mul_f32_e32 v10, v12, v11
	v_mul_f32_e32 v5, v5, v13
	v_mul_f32_e32 v7, v10, v7
	v_cvt_pk_bf16_f32 v7, v5, v7
	v_lshlrev_b32_e32 v5, 16, v80
	v_and_b32_e32 v11, 0xffff0000, v80
	v_mul_f32_e32 v10, 0xbfb8aa3b, v5
	v_mul_f32_e32 v12, 0xbfb8aa3b, v11
	v_exp_f32_e32 v10, v10
	v_exp_f32_e32 v12, v12
	v_lshlrev_b32_e32 v13, 16, v8
	v_and_b32_e32 v8, 0xffff0000, v8
	v_add_f32_e32 v10, 1.0, v10
	v_add_f32_e32 v12, 1.0, v12
	v_rcp_f32_e32 v10, v10
	v_rcp_f32_e32 v12, v12
	v_mul_f32_e32 v5, v10, v5
	v_mul_f32_e32 v10, v12, v11
	v_mul_f32_e32 v5, v5, v13
	v_mul_f32_e32 v8, v10, v8
	v_cvt_pk_bf16_f32 v8, v5, v8
	v_lshlrev_b32_e32 v5, 16, v81
	v_and_b32_e32 v11, 0xffff0000, v81
	v_mul_f32_e32 v10, 0xbfb8aa3b, v5
	v_mul_f32_e32 v12, 0xbfb8aa3b, v11
	v_exp_f32_e32 v10, v10
	v_exp_f32_e32 v12, v12
	v_lshlrev_b32_e32 v13, 16, v9
	v_and_b32_e32 v9, 0xffff0000, v9
	v_add_f32_e32 v10, 1.0, v10
	v_add_f32_e32 v12, 1.0, v12
	v_rcp_f32_e32 v10, v10
	v_rcp_f32_e32 v12, v12
	v_mul_f32_e32 v5, v10, v5
	v_mul_f32_e32 v10, v12, v11
	v_mul_f32_e32 v5, v5, v13
	v_mul_f32_e32 v9, v10, v9
	v_add_co_u32_e32 v10, vcc, s56, v2
	v_cvt_pk_bf16_f32 v9, v5, v9
	v_add_u32_e32 v5, 20, v4
	s_nop 0
	v_addc_co_u32_e32 v11, vcc, 0, v3, vcc
	global_store_dwordx4 v[10:11], v[6:9], off
	v_and_b32_e32 v11, 0xffff0000, v74
	v_mul_f32_e32 v12, 0xbfb8aa3b, v11
	v_lshlrev_b32_e32 v6, 8, v5
	v_xor_b32_e32 v5, v5, v82
	v_lshlrev_b32_e32 v5, 4, v5
	v_and_b32_e32 v5, 0xf0, v5
	v_add3_u32 v5, s22, v6, v5
	ds_read_b128 v[6:9], v5
	v_lshlrev_b32_e32 v5, 16, v74
	v_mul_f32_e32 v10, 0xbfb8aa3b, v5
	v_exp_f32_e32 v10, v10
	v_exp_f32_e32 v12, v12
	s_waitcnt lgkmcnt(0)
; #define LAS __attribute__((address_space(3)))
; DI unsigned cvt_pk_bf16(float lo, float hi) { unsigned r; asm volatile("v_cvt_pk_bf16_f32 %0, %1, %2" : "=v"(r) : "v"(lo), "v"(hi)); return r; }
; DI float bflo(unsigned w) { return __uint_as_float(w << 16); }
; DI float bfhi(unsigned w) { return __uint_as_float(w & 0xffff0000u); }
; DI float silu_fast(float z) { return z * __builtin_amdgcn_rcpf(1.0f + __builtin_amdgcn_exp2f(-z * LOG2E)); }
; DI void phase_attn(const Params& P, int l, LAS unsigned char* lds) {
;     ...
;           bf16_t* op = MI + (tokw + (lane >> 4)) * DM + g * 128 + (lane & 15) * 8;
; #pragma unroll
;           for (int it = 0; it < 8; ++it) { const int row = it * 4 + (lsw >> 4);
;               const u32x4 ov = *(const LAS u32x4*)(stg + row * 256 + (((lsw & 15) ^ (row & 15)) << 4)); const u32x4 z = zz[it]; u32x4 w;
; #pragma unroll
;               for (int q = 0; q < 4; ++q) w[q] = cvt_pk_bf16(bflo(ov[q]) * silu_fast(bflo(z[q])), bfhi(ov[q]) * silu_fast(bfhi(z[q])));
;               *(u32x4*)(op + (size_t)it * 4 * DM) = w; if (it & 1) __builtin_amdgcn_sched_barrier(0); } }
	v_lshlrev_b32_e32 v13, 16, v6
	v_and_b32_e32 v6, 0xffff0000, v6
	v_add_f32_e32 v10, 1.0, v10
	v_add_f32_e32 v12, 1.0, v12
	v_rcp_f32_e32 v10, v10
	v_rcp_f32_e32 v12, v12
	v_mul_f32_e32 v5, v10, v5
	v_mul_f32_e32 v10, v12, v11
	v_mul_f32_e32 v5, v5, v13
	v_mul_f32_e32 v6, v10, v6
	v_cvt_pk_bf16_f32 v6, v5, v6
	v_lshlrev_b32_e32 v5, 16, v75
	v_and_b32_e32 v11, 0xffff0000, v75
	v_mul_f32_e32 v10, 0xbfb8aa3b, v5
	v_mul_f32_e32 v12, 0xbfb8aa3b, v11
	v_exp_f32_e32 v10, v10
	v_exp_f32_e32 v12, v12
	v_lshlrev_b32_e32 v13, 16, v7
	v_and_b32_e32 v7, 0xffff0000, v7
	v_add_f32_e32 v10, 1.0, v10
	v_add_f32_e32 v12, 1.0, v12
	v_rcp_f32_e32 v10, v10
	v_rcp_f32_e32 v12, v12
	v_mul_f32_e32 v5, v10, v5
	v_mul_f32_e32 v10, v12, v11
	v_mul_f32_e32 v5, v5, v13
	v_mul_f32_e32 v7, v10, v7
	v_cvt_pk_bf16_f32 v7, v5, v7
	v_lshlrev_b32_e32 v5, 16, v76
	v_and_b32_e32 v11, 0xffff0000, v76
	v_mul_f32_e32 v10, 0xbfb8aa3b, v5
	v_mul_f32_e32 v12, 0xbfb8aa3b, v11
	v_exp_f32_e32 v10, v10
	v_exp_f32_e32 v12, v12
	v_lshlrev_b32_e32 v13, 16, v8
	v_and_b32_e32 v8, 0xffff0000, v8
	v_add_f32_e32 v10, 1.0, v10
	v_add_f32_e32 v12, 1.0, v12
	v_rcp_f32_e32 v10, v10
	v_rcp_f32_e32 v12, v12
	v_mul_f32_e32 v5, v10, v5
	v_mul_f32_e32 v10, v12, v11
	v_mul_f32_e32 v5, v5, v13
	v_mul_f32_e32 v8, v10, v8
	v_cvt_pk_bf16_f32 v8, v5, v8
	v_lshlrev_b32_e32 v5, 16, v77
	v_and_b32_e32 v11, 0xffff0000, v77
	v_mul_f32_e32 v10, 0xbfb8aa3b, v5
	v_mul_f32_e32 v12, 0xbfb8aa3b, v11
	v_exp_f32_e32 v10, v10
	v_exp_f32_e32 v12, v12
	v_lshlrev_b32_e32 v13, 16, v9
	v_and_b32_e32 v9, 0xffff0000, v9
	v_add_f32_e32 v10, 1.0, v10
	v_add_f32_e32 v12, 1.0, v12
	v_rcp_f32_e32 v10, v10
	v_rcp_f32_e32 v12, v12
	v_mul_f32_e32 v5, v10, v5
	v_mul_f32_e32 v10, v12, v11
	v_mul_f32_e32 v9, v10, v9
	v_add_co_u32_e32 v10, vcc, s74, v2
	v_mul_f32_e32 v5, v5, v13
	s_nop 0
	v_addc_co_u32_e32 v11, vcc, 0, v3, vcc
	v_cvt_pk_bf16_f32 v9, v5, v9
	global_store_dwordx4 v[10:11], v[6:9], off
	v_add_u32_e32 v5, 24, v4
	s_nop 0
	v_lshlrev_b32_e32 v6, 8, v5
	v_xor_b32_e32 v5, v5, v82
	v_lshlrev_b32_e32 v5, 4, v5
	v_and_b32_e32 v5, 0xf0, v5
	v_add3_u32 v5, s22, v6, v5
	ds_read_b128 v[6:9], v5
	v_lshlrev_b32_e32 v5, 16, v70
	v_and_b32_e32 v11, 0xffff0000, v70
	v_mul_f32_e32 v10, 0xbfb8aa3b, v5
	v_mul_f32_e32 v12, 0xbfb8aa3b, v11
	v_exp_f32_e32 v10, v10
	v_exp_f32_e32 v12, v12
	s_waitcnt lgkmcnt(0)
	v_lshlrev_b32_e32 v13, 16, v6
	v_and_b32_e32 v6, 0xffff0000, v6
	v_add_f32_e32 v10, 1.0, v10
	v_add_f32_e32 v12, 1.0, v12
	v_rcp_f32_e32 v10, v10
	v_rcp_f32_e32 v12, v12
	v_add_u32_e32 v4, 28, v4
	v_mul_f32_e32 v5, v10, v5
	v_mul_f32_e32 v10, v12, v11
	v_mul_f32_e32 v5, v5, v13
	v_mul_f32_e32 v6, v10, v6
	v_cvt_pk_bf16_f32 v6, v5, v6
	v_lshlrev_b32_e32 v5, 16, v71
	v_and_b32_e32 v11, 0xffff0000, v71
	v_mul_f32_e32 v10, 0xbfb8aa3b, v5
	v_mul_f32_e32 v12, 0xbfb8aa3b, v11
	v_exp_f32_e32 v10, v10
	v_exp_f32_e32 v12, v12
	v_lshlrev_b32_e32 v13, 16, v7
	v_and_b32_e32 v7, 0xffff0000, v7
	v_add_f32_e32 v10, 1.0, v10
	v_add_f32_e32 v12, 1.0, v12
	v_rcp_f32_e32 v10, v10
	v_rcp_f32_e32 v12, v12
	v_mul_f32_e32 v5, v10, v5
	v_mul_f32_e32 v10, v12, v11
	v_mul_f32_e32 v5, v5, v13
	v_mul_f32_e32 v7, v10, v7
	v_cvt_pk_bf16_f32 v7, v5, v7
	v_lshlrev_b32_e32 v5, 16, v72
	v_and_b32_e32 v11, 0xffff0000, v72
	v_mul_f32_e32 v10, 0xbfb8aa3b, v5
	v_mul_f32_e32 v12, 0xbfb8aa3b, v11
	v_exp_f32_e32 v10, v10
	v_exp_f32_e32 v12, v12
	v_lshlrev_b32_e32 v13, 16, v8
	v_and_b32_e32 v8, 0xffff0000, v8
	v_add_f32_e32 v10, 1.0, v10
	v_add_f32_e32 v12, 1.0, v12
	v_rcp_f32_e32 v10, v10
	v_rcp_f32_e32 v12, v12
	v_mul_f32_e32 v5, v10, v5
	v_mul_f32_e32 v10, v12, v11
	v_mul_f32_e32 v5, v5, v13
	v_mul_f32_e32 v8, v10, v8
	v_cvt_pk_bf16_f32 v8, v5, v8
	v_lshlrev_b32_e32 v5, 16, v73
	v_and_b32_e32 v11, 0xffff0000, v73
	v_mul_f32_e32 v10, 0xbfb8aa3b, v5
	v_mul_f32_e32 v12, 0xbfb8aa3b, v11
	v_exp_f32_e32 v10, v10
	v_exp_f32_e32 v12, v12
	v_lshlrev_b32_e32 v13, 16, v9
	v_and_b32_e32 v9, 0xffff0000, v9
	v_add_f32_e32 v10, 1.0, v10
	v_add_f32_e32 v12, 1.0, v12
	v_rcp_f32_e32 v10, v10
	v_rcp_f32_e32 v12, v12
	v_mul_f32_e32 v5, v10, v5
	v_mul_f32_e32 v10, v12, v11
	v_mul_f32_e32 v9, v10, v9
	v_add_co_u32_e32 v10, vcc, s81, v2
	v_mul_f32_e32 v5, v5, v13
	s_nop 0
	v_addc_co_u32_e32 v11, vcc, 0, v3, vcc
	v_cvt_pk_bf16_f32 v9, v5, v9
	global_store_dwordx4 v[10:11], v[6:9], off
	v_and_b32_e32 v10, 0xffff0000, v66
	v_mul_f32_e32 v11, 0xbfb8aa3b, v10
	v_lshlrev_b32_e32 v8, 16, v66
	v_mul_f32_e32 v9, 0xbfb8aa3b, v8
	v_lshlrev_b32_e32 v5, 8, v4
	v_xor_b32_e32 v4, v4, v82
	v_exp_f32_e32 v9, v9
	v_exp_f32_e32 v11, v11
	v_lshlrev_b32_e32 v4, 4, v4
	v_and_b32_e32 v4, 0xf0, v4
	v_add3_u32 v4, s22, v5, v4
	ds_read_b128 v[4:7], v4
	v_add_f32_e32 v9, 1.0, v9
	v_add_f32_e32 v11, 1.0, v11
	v_rcp_f32_e32 v9, v9
	v_rcp_f32_e32 v11, v11
	s_waitcnt lgkmcnt(0)
; #define LAS __attribute__((address_space(3)))
; DI unsigned cvt_pk_bf16(float lo, float hi) { unsigned r; asm volatile("v_cvt_pk_bf16_f32 %0, %1, %2" : "=v"(r) : "v"(lo), "v"(hi)); return r; }
; DI float bflo(unsigned w) { return __uint_as_float(w << 16); }
; DI float bfhi(unsigned w) { return __uint_as_float(w & 0xffff0000u); }
; DI float silu_fast(float z) { return z * __builtin_amdgcn_rcpf(1.0f + __builtin_amdgcn_exp2f(-z * LOG2E)); }
; DI void phase_attn(const Params& P, int l, LAS unsigned char* lds) {
;     ...
;           for (int it = 0; it < 8; ++it) { const int row = it * 4 + (lsw >> 4);
;               const u32x4 ov = *(const LAS u32x4*)(stg + row * 256 + (((lsw & 15) ^ (row & 15)) << 4)); const u32x4 z = zz[it]; u32x4 w;
; #pragma unroll
;               for (int q = 0; q < 4; ++q) w[q] = cvt_pk_bf16(bflo(ov[q]) * silu_fast(bflo(z[q])), bfhi(ov[q]) * silu_fast(bfhi(z[q])));
;               *(u32x4*)(op + (size_t)it * 4 * DM) = w; if (it & 1) __builtin_amdgcn_sched_barrier(0); } }
;         item = inext; inext = slot[2];
	v_lshlrev_b32_e32 v12, 16, v4
	v_and_b32_e32 v4, 0xffff0000, v4
	v_mul_f32_e32 v8, v9, v8
	v_mul_f32_e32 v9, v11, v10
	v_mul_f32_e32 v8, v8, v12
	v_mul_f32_e32 v4, v9, v4
	v_cvt_pk_bf16_f32 v4, v8, v4
	v_lshlrev_b32_e32 v8, 16, v67
	v_and_b32_e32 v10, 0xffff0000, v67
	v_mul_f32_e32 v9, 0xbfb8aa3b, v8
	v_mul_f32_e32 v11, 0xbfb8aa3b, v10
	v_exp_f32_e32 v9, v9
	v_exp_f32_e32 v11, v11
	v_lshlrev_b32_e32 v12, 16, v5
	v_and_b32_e32 v5, 0xffff0000, v5
	v_add_f32_e32 v9, 1.0, v9
	v_add_f32_e32 v11, 1.0, v11
	v_rcp_f32_e32 v9, v9
	v_rcp_f32_e32 v11, v11
	v_add_co_u32_e32 v2, vcc, 0x1c000, v2
	v_mul_f32_e32 v8, v9, v8
	v_mul_f32_e32 v9, v11, v10
	v_mul_f32_e32 v8, v8, v12
	v_mul_f32_e32 v5, v9, v5
	v_cvt_pk_bf16_f32 v5, v8, v5
	v_lshlrev_b32_e32 v8, 16, v68
	v_and_b32_e32 v10, 0xffff0000, v68
	v_mul_f32_e32 v9, 0xbfb8aa3b, v8
	v_mul_f32_e32 v11, 0xbfb8aa3b, v10
	v_exp_f32_e32 v9, v9
	v_exp_f32_e32 v11, v11
	v_lshlrev_b32_e32 v12, 16, v6
	v_and_b32_e32 v6, 0xffff0000, v6
	v_add_f32_e32 v9, 1.0, v9
	v_add_f32_e32 v11, 1.0, v11
	v_rcp_f32_e32 v9, v9
	v_rcp_f32_e32 v11, v11
	v_addc_co_u32_e32 v3, vcc, 0, v3, vcc
	v_mul_f32_e32 v8, v9, v8
	v_mul_f32_e32 v9, v11, v10
	v_mul_f32_e32 v8, v8, v12
	v_mul_f32_e32 v6, v9, v6
	v_cvt_pk_bf16_f32 v6, v8, v6
	v_lshlrev_b32_e32 v8, 16, v69
	v_and_b32_e32 v10, 0xffff0000, v69
	v_mul_f32_e32 v9, 0xbfb8aa3b, v8
	v_mul_f32_e32 v11, 0xbfb8aa3b, v10
	v_exp_f32_e32 v9, v9
	v_exp_f32_e32 v11, v11
	v_lshlrev_b32_e32 v12, 16, v7
	v_and_b32_e32 v7, 0xffff0000, v7
	v_add_f32_e32 v9, 1.0, v9
	v_add_f32_e32 v11, 1.0, v11
	v_rcp_f32_e32 v9, v9
	v_rcp_f32_e32 v11, v11
	v_mul_f32_e32 v8, v9, v8
	v_mul_f32_e32 v9, v11, v10
	v_mul_f32_e32 v7, v9, v7
	v_mul_f32_e32 v8, v8, v12
	v_cvt_pk_bf16_f32 v7, v8, v7
	global_store_dwordx4 v[2:3], v[4:7], off
	v_mov_b32_e32 v2, s55
	ds_read_b32 v2, v2
	s_andn2_b64 vcc, exec, s[20:21]
	s_mov_b32 s26, s36
	s_waitcnt lgkmcnt(0)
	v_readfirstlane_b32 s4, v2
	s_mov_b32 s36, s4
	s_and_b32 s95, s36, 3
	s_lshr_b32 s96, s36, 2
	s_mul_i32 s97, s96, 0x889
	s_lshr_b32 s97, s97, 16
	s_mul_i32 s69, s97, 30
	s_sub_i32 s69, s96, s69
	s_add_i32 s69, s69, 1
	s_lshl_b32 s97, s97, 7
	s_lshl_b32 s69, s69, 2
	s_or_b32 s97, s97, s69
	s_or_b32 s97, s97, s95
	s_sub_i32 s96, s36, 0x4b0
	s_lshr_b32 s69, s96, 2
	s_and_b32 s96, s69, 1
	s_mul_i32 s96, s96, 0x7c
	s_lshr_b32 s69, s69, 1
	s_lshl_b32 s69, s69, 7
	s_or_b32 s69, s69, s96
	s_or_b32 s69, s69, s95
	s_cmp_lt_u32 s36, 0x4b0
	s_cselect_b32 s97, s97, s69
	s_cmp_lt_u32 s36, 0x500
	s_cselect_b32 s36, s97, s36
	s_cbranch_vccz .LBB0_1062
